# nt loads too in the LayerNorm phases (nt stores in LN + prologue kept), on aligned GEMM K-loops + MMA-path cleanup
# speedup vs baseline: 1.0075x; 1.0006x over previous
.LBB0_835:
	global_load_dwordx4 v[10:13], v[6:7], off nt
	global_load_dwordx4 v[14:17], v[4:5], off nt
	v_add_u32_e32 v1, 0x200, v1
	v_cmp_lt_i32_e32 vcc, s16, v1
	v_lshl_add_u64 v[4:5], v[4:5], 0, s[10:11]
	v_lshl_add_u64 v[6:7], v[6:7], 0, s[10:11]
	s_or_b64 s[8:9], vcc, s[8:9]
	s_waitcnt vmcnt(1)
	ds_write_b128 v8, v[10:13]
	s_waitcnt vmcnt(0)
	ds_write_b128 v8, v[14:17] offset:16384
	v_add_u32_e32 v8, 0x2000, v8
	s_andn2_b64 exec, exec, s[8:9]
	s_cbranch_execnz .LBB0_835

.LBB0_838:
	v_cmp_lt_i32_e32 vcc, v106, v105
	v_lshl_add_u64 v[4:5], s[14:15], 0, v[34:35]
	v_lshl_add_u64 v[2:3], s[30:31], 0, v[36:37]
	v_cndmask_b32_e32 v6, v104, v106, vcc
	v_cmp_lt_i32_e32 vcc, v107, v105
	v_lshl_add_u64 v[12:13], v[4:5], 0, s[36:37]
	global_load_dwordx4 v[72:75], v36, s[30:31]
	global_load_dwordx4 v[68:71], v36, s[30:31] offset:1024
	global_load_dwordx4 v[76:79], v36, s[30:31] offset:2048
	global_load_dwordx4 v[80:83], v36, s[30:31] offset:3072
	v_cndmask_b32_e32 v7, v104, v107, vcc
	v_cmp_lt_i32_e32 vcc, v108, v105
	v_lshlrev_b32_e32 v131, 2, v6
	global_load_dwordx2 v[42:43], v[12:13], off offset:512 nt
	global_load_dwordx2 v[46:47], v[12:13], off offset:1024 nt
	global_load_dwordx2 v[50:51], v[12:13], off offset:1536 nt
	global_load_dwordx2 v[54:55], v[12:13], off offset:2048 nt
	global_load_dwordx2 v[58:59], v[12:13], off offset:2560 nt
	global_load_dwordx2 v[62:63], v[12:13], off offset:3072 nt
	v_cndmask_b32_e32 v8, v104, v108, vcc
	v_cmp_lt_i32_e32 vcc, v109, v105
	v_lshlrev_b32_e32 v178, 2, v7
	v_lshlrev_b32_e32 v179, 2, v8
	v_cndmask_b32_e32 v9, v104, v109, vcc
	v_cmp_lt_i32_e32 vcc, v110, v105
	global_load_dwordx2 v[160:161], v[12:13], off offset:3584 nt
	v_lshlrev_b32_e32 v180, 2, v9
	v_cndmask_b32_e32 v10, v104, v110, vcc
	v_cmp_lt_i32_e32 vcc, v111, v105
	v_add_co_u32_e64 v38, s[4:5], s3, v4
	s_nop 0
	v_cndmask_b32_e32 v11, v104, v111, vcc
	v_add_co_u32_e32 v14, vcc, 0xf8000000, v4
	v_addc_co_u32_e64 v39, s[4:5], 0, v5, s[4:5]
	s_nop 0
	v_addc_co_u32_e32 v15, vcc, -1, v5, vcc
	v_add_co_u32_e32 v6, vcc, s3, v2
	global_load_dwordx2 v[66:67], v[14:15], off nt
	s_nop 0
	v_addc_co_u32_e32 v7, vcc, 0, v3, vcc
	v_add_co_u32_e32 v8, vcc, s7, v2
	global_load_dwordx4 v[84:87], v[6:7], off offset:1024 nt
	global_load_dwordx4 v[88:91], v[6:7], off offset:2048 nt
	global_load_dwordx4 v[92:95], v[6:7], off offset:3072 nt
	v_addc_co_u32_e32 v9, vcc, 0, v3, vcc
	v_add_co_u32_e32 v6, vcc, s9, v4
	global_load_dwordx4 v[96:99], v[8:9], off offset:-4096 nt
	global_load_dwordx4 v[100:103], v[8:9], off nt
	v_addc_co_u32_e32 v7, vcc, -1, v5, vcc
	v_add_co_u32_e32 v4, vcc, s18, v4
	global_load_dwordx4 v[132:135], v[8:9], off offset:1024 nt
	global_load_dwordx4 v[136:139], v[8:9], off offset:2048 nt
	global_load_dwordx4 v[140:143], v[8:9], off offset:3072 nt
	v_addc_co_u32_e32 v5, vcc, -1, v5, vcc
	global_load_dwordx2 v[162:163], v[6:7], off nt
	global_load_dwordx2 v[164:165], v[4:5], off offset:-3584 nt
	global_load_dwordx2 v[166:167], v[4:5], off offset:-3072 nt
	global_load_dwordx2 v[168:169], v[4:5], off offset:-2560 nt
	v_add_co_u32_e32 v2, vcc, s19, v2
	v_lshlrev_b32_e32 v181, 2, v10
	s_nop 0
	v_addc_co_u32_e32 v3, vcc, 0, v3, vcc
	global_load_dwordx2 v[170:171], v[4:5], off offset:-2048 nt
	global_load_dwordx2 v[172:173], v[4:5], off offset:-1536 nt
	global_load_dwordx2 v[174:175], v[4:5], off offset:-1024 nt
	global_load_dwordx2 v[176:177], v[4:5], off offset:-512 nt
	global_load_dwordx4 v[144:147], v[2:3], off nt
	global_load_dwordx4 v[148:151], v[2:3], off offset:1024 nt
	global_load_dwordx4 v[152:155], v[2:3], off offset:2048 nt
	global_load_dwordx4 v[156:159], v[2:3], off offset:3072 nt
	v_lshlrev_b32_e32 v182, 2, v11
	ds_read_b128 v[10:13], v1
	ds_read_b128 v[2:5], v1 offset:1024
	ds_read_b128 v[26:29], v1 offset:16384
	ds_read_b128 v[18:21], v1 offset:17408
	ds_read_b128 v[14:17], v1 offset:2048
	ds_read_b128 v[6:9], v1 offset:3072
	ds_read_b128 v[30:33], v1 offset:18432
	ds_read_b128 v[22:25], v1 offset:19456
	v_mov_b32_e32 v115, 0
	v_mov_b32_e32 v116, 0
	v_mov_b32_e32 v117, 0
	v_mov_b32_e32 v119, 0
	v_mov_b32_e32 v118, 0
	v_mov_b32_e32 v120, 0
	v_mov_b32_e32 v121, 0
	v_mov_b32_e32 v123, 0
	v_mov_b32_e32 v122, 0
	v_mov_b32_e32 v124, 0
	v_mov_b32_e32 v125, 0
	v_mov_b32_e32 v127, 0
	v_mov_b32_e32 v126, 0
	v_mov_b32_e32 v128, 0
	v_mov_b32_e32 v129, 0
	v_mov_b32_e32 v130, 0
	s_add_i32 s6, s6, s8
	s_waitcnt vmcnt(27)
	v_lshlrev_b32_e32 v40, 16, v42
	v_and_b32_e32 v41, 0xffff0000, v42
	v_lshlrev_b32_e32 v42, 16, v43
	v_and_b32_e32 v43, 0xffff0000, v43
	s_waitcnt vmcnt(26)
	v_lshlrev_b32_e32 v44, 16, v46
	v_and_b32_e32 v45, 0xffff0000, v46
	v_lshlrev_b32_e32 v46, 16, v47
	v_and_b32_e32 v47, 0xffff0000, v47
	s_waitcnt vmcnt(25)
	v_lshlrev_b32_e32 v48, 16, v50
	v_and_b32_e32 v49, 0xffff0000, v50
	v_lshlrev_b32_e32 v50, 16, v51
	v_and_b32_e32 v51, 0xffff0000, v51
	s_waitcnt vmcnt(23)
	v_lshlrev_b32_e32 v56, 16, v58
	v_and_b32_e32 v57, 0xffff0000, v58
	v_lshlrev_b32_e32 v58, 16, v59
	v_and_b32_e32 v59, 0xffff0000, v59
	v_fmac_f32_e32 v40, 0x3fb504f3, v68
	v_fmac_f32_e32 v41, 0x3fb504f3, v69
	v_fmac_f32_e32 v42, 0x3fb504f3, v70
	v_fmac_f32_e32 v43, 0x3fb504f3, v71
	v_fmac_f32_e32 v46, 0x3fb504f3, v78
	v_fmac_f32_e32 v47, 0x3fb504f3, v79
	v_fmac_f32_e32 v48, 0x3fb504f3, v80
	v_fmac_f32_e32 v49, 0x3fb504f3, v81
	v_fmac_f32_e32 v50, 0x3fb504f3, v82
	v_fmac_f32_e32 v51, 0x3fb504f3, v83
	s_waitcnt vmcnt(21)
	v_lshlrev_b32_e32 v68, 16, v160
	s_waitcnt vmcnt(20)
	v_lshlrev_b32_e32 v64, 16, v66
	v_and_b32_e32 v65, 0xffff0000, v66
	v_lshlrev_b32_e32 v66, 16, v67
	v_and_b32_e32 v67, 0xffff0000, v67
	v_fmac_f32_e32 v64, 0x3fb504f3, v72
	v_fmac_f32_e32 v65, 0x3fb504f3, v73
	v_fmac_f32_e32 v66, 0x3fb504f3, v74
	v_fmac_f32_e32 v67, 0x3fb504f3, v75
	v_and_b32_e32 v69, 0xffff0000, v160
	v_lshlrev_b32_e32 v70, 16, v161
	v_and_b32_e32 v71, 0xffff0000, v161
	v_add_f32_e32 v72, v40, v41
	v_add_f32_e32 v73, v42, v43
	s_waitcnt vmcnt(19)
	v_fmac_f32_e32 v56, 0x3fb504f3, v84
	v_fmac_f32_e32 v57, 0x3fb504f3, v85
	v_fmac_f32_e32 v58, 0x3fb504f3, v86
	v_fmac_f32_e32 v59, 0x3fb504f3, v87
	v_add_f32_e32 v78, v64, v65
	v_add_f32_e32 v79, v66, v67
	v_fmac_f32_e32 v44, 0x3fb504f3, v76
	v_fmac_f32_e32 v45, 0x3fb504f3, v77
	v_add_f32_e32 v76, v48, v49
	v_add_f32_e32 v77, v50, v51
	s_waitcnt vmcnt(17)
	v_fmac_f32_e32 v68, 0x3fb504f3, v92
	v_fmac_f32_e32 v69, 0x3fb504f3, v93
	v_fmac_f32_e32 v70, 0x3fb504f3, v94
	v_fmac_f32_e32 v71, 0x3fb504f3, v95
	v_add_f32_e32 v160, v72, v73
	v_add_f32_e32 v72, v56, v57
	v_add_f32_e32 v73, v58, v59
	v_add_f32_e32 v78, v78, v79
	v_lshlrev_b32_e32 v52, 16, v54
	v_and_b32_e32 v53, 0xffff0000, v54
	v_lshlrev_b32_e32 v54, 16, v55
	v_and_b32_e32 v55, 0xffff0000, v55
	v_lshlrev_b32_e32 v60, 16, v62
	v_and_b32_e32 v61, 0xffff0000, v62
	v_lshlrev_b32_e32 v62, 16, v63
	v_and_b32_e32 v63, 0xffff0000, v63
	v_add_f32_e32 v74, v44, v45
	v_add_f32_e32 v75, v46, v47
	v_add_f32_e32 v183, v76, v77
	v_add_f32_e32 v76, v68, v69
	v_add_f32_e32 v77, v70, v71
	v_add_f32_e32 v184, v72, v73
	s_waitcnt vmcnt(11)
	v_lshlrev_b32_e32 v72, 16, v162
	v_and_b32_e32 v73, 0xffff0000, v162
	v_add_f32_e32 v162, 0, v78
	v_fmac_f32_e32 v60, 0x3fb504f3, v88
	v_fmac_f32_e32 v61, 0x3fb504f3, v89
	v_fmac_f32_e32 v62, 0x3fb504f3, v90
	v_fmac_f32_e32 v63, 0x3fb504f3, v91
	v_add_f32_e32 v161, v74, v75
	v_fmac_f32_e32 v52, 0x3fb504f3, v96
	v_fmac_f32_e32 v53, 0x3fb504f3, v97
	v_fmac_f32_e32 v54, 0x3fb504f3, v98
	v_fmac_f32_e32 v55, 0x3fb504f3, v99
	v_add_f32_e32 v186, v76, v77
	s_waitcnt vmcnt(10)
	v_lshlrev_b32_e32 v76, 16, v164
	v_add_f32_e32 v160, v162, v160
	v_add_f32_e32 v74, v60, v61
	v_add_f32_e32 v75, v62, v63
	v_add_f32_e32 v79, v52, v53
	v_add_f32_e32 v80, v54, v55
	v_fmac_f32_e32 v76, 0x3fb504f3, v132
	v_add_f32_e32 v132, v160, v161
	v_add_f32_e32 v185, v74, v75
	v_lshlrev_b32_e32 v74, 16, v163
	v_and_b32_e32 v75, 0xffff0000, v163
	v_add_f32_e32 v163, v79, v80
	v_add_f32_e32 v132, v132, v183
	v_add_f32_e32 v132, v132, v163
	v_fmac_f32_e32 v72, 0x3fb504f3, v100
	v_fmac_f32_e32 v73, 0x3fb504f3, v101
	v_fmac_f32_e32 v74, 0x3fb504f3, v102
	v_fmac_f32_e32 v75, 0x3fb504f3, v103
	v_and_b32_e32 v77, 0xffff0000, v164
	v_lshlrev_b32_e32 v78, 16, v165
	v_and_b32_e32 v79, 0xffff0000, v165
	v_add_f32_e32 v132, v132, v184
	s_waitcnt vmcnt(9)
	v_lshlrev_b32_e32 v80, 16, v166
	v_and_b32_e32 v81, 0xffff0000, v166
	v_lshlrev_b32_e32 v82, 16, v167
	v_and_b32_e32 v83, 0xffff0000, v167
	v_add_f32_e32 v162, v72, v73
	v_add_f32_e32 v164, v74, v75
	v_fmac_f32_e32 v77, 0x3fb504f3, v133
	v_fmac_f32_e32 v78, 0x3fb504f3, v134
	v_fmac_f32_e32 v79, 0x3fb504f3, v135
	v_add_f32_e32 v132, v132, v185
	s_waitcnt vmcnt(8)
	v_lshlrev_b32_e32 v84, 16, v168
	v_and_b32_e32 v85, 0xffff0000, v168
	v_lshlrev_b32_e32 v86, 16, v169
	v_and_b32_e32 v87, 0xffff0000, v169
	v_fmac_f32_e32 v80, 0x3fb504f3, v136
	v_fmac_f32_e32 v81, 0x3fb504f3, v137
	v_fmac_f32_e32 v82, 0x3fb504f3, v138
	v_fmac_f32_e32 v83, 0x3fb504f3, v139
	v_add_f32_e32 v133, v162, v164
	v_add_f32_e32 v134, v76, v77
	v_add_f32_e32 v135, v78, v79
	v_add_f32_e32 v132, v132, v186
	s_waitcnt vmcnt(7)
	v_lshlrev_b32_e32 v88, 16, v170
	v_and_b32_e32 v89, 0xffff0000, v170
	v_lshlrev_b32_e32 v90, 16, v171
	v_and_b32_e32 v91, 0xffff0000, v171
	v_fmac_f32_e32 v84, 0x3fb504f3, v140
	v_fmac_f32_e32 v85, 0x3fb504f3, v141
	v_fmac_f32_e32 v86, 0x3fb504f3, v142
	v_fmac_f32_e32 v87, 0x3fb504f3, v143
	v_add_f32_e32 v136, v80, v81
	v_add_f32_e32 v137, v82, v83
	v_add_f32_e32 v134, v134, v135
	v_add_f32_e32 v132, v132, v133
	s_waitcnt vmcnt(6)
	v_lshlrev_b32_e32 v92, 16, v172
	v_and_b32_e32 v93, 0xffff0000, v172
	v_lshlrev_b32_e32 v94, 16, v173
	v_and_b32_e32 v95, 0xffff0000, v173
	s_waitcnt vmcnt(3)
	v_fmac_f32_e32 v88, 0x3fb504f3, v144
	v_fmac_f32_e32 v89, 0x3fb504f3, v145
	v_fmac_f32_e32 v90, 0x3fb504f3, v146
	v_fmac_f32_e32 v91, 0x3fb504f3, v147
	v_add_f32_e32 v138, v84, v85
	v_add_f32_e32 v139, v86, v87
	v_add_f32_e32 v135, v136, v137
	v_add_f32_e32 v132, v132, v134
	v_lshlrev_b32_e32 v96, 16, v174
	v_and_b32_e32 v97, 0xffff0000, v174
	v_lshlrev_b32_e32 v98, 16, v175
	v_and_b32_e32 v99, 0xffff0000, v175
	s_waitcnt vmcnt(2)
	v_fmac_f32_e32 v92, 0x3fb504f3, v148
	v_fmac_f32_e32 v93, 0x3fb504f3, v149
	v_fmac_f32_e32 v94, 0x3fb504f3, v150
	v_fmac_f32_e32 v95, 0x3fb504f3, v151
	v_add_f32_e32 v140, v88, v89
	v_add_f32_e32 v141, v90, v91
	v_add_f32_e32 v136, v138, v139
	v_add_f32_e32 v132, v132, v135
	v_lshlrev_b32_e32 v100, 16, v176
	v_and_b32_e32 v101, 0xffff0000, v176
	v_lshlrev_b32_e32 v102, 16, v177
	v_and_b32_e32 v103, 0xffff0000, v177
	s_waitcnt vmcnt(1)
	v_fmac_f32_e32 v96, 0x3fb504f3, v152
	v_fmac_f32_e32 v97, 0x3fb504f3, v153
	v_fmac_f32_e32 v98, 0x3fb504f3, v154
	v_fmac_f32_e32 v99, 0x3fb504f3, v155
	v_add_f32_e32 v142, v92, v93
	v_add_f32_e32 v143, v94, v95
	v_add_f32_e32 v137, v140, v141
	v_add_f32_e32 v132, v132, v136
	s_waitcnt vmcnt(0)
	v_fmac_f32_e32 v100, 0x3fb504f3, v156
	v_fmac_f32_e32 v101, 0x3fb504f3, v157
	v_fmac_f32_e32 v102, 0x3fb504f3, v158
	v_fmac_f32_e32 v103, 0x3fb504f3, v159
	v_add_f32_e32 v144, v96, v97
	v_add_f32_e32 v145, v98, v99
	v_add_f32_e32 v138, v142, v143
	v_add_f32_e32 v132, v132, v137
	v_add_f32_e32 v146, v100, v101
	v_add_f32_e32 v147, v102, v103
	v_add_f32_e32 v139, v144, v145
	v_add_f32_e32 v132, v132, v138
	v_add_f32_e32 v140, v146, v147
	v_add_f32_e32 v132, v132, v139
	v_add_f32_e32 v132, v132, v140
	ds_bpermute_b32 v133, v131, v132
	s_waitcnt lgkmcnt(0)
	v_add_f32_e32 v132, v132, v133
	ds_bpermute_b32 v133, v178, v132
	s_waitcnt lgkmcnt(0)
	v_add_f32_e32 v132, v132, v133
	ds_bpermute_b32 v133, v179, v132
	s_waitcnt lgkmcnt(0)
	v_add_f32_e32 v132, v132, v133
	ds_bpermute_b32 v133, v180, v132
	s_waitcnt lgkmcnt(0)
	v_add_f32_e32 v132, v132, v133
	ds_bpermute_b32 v133, v181, v132
	s_waitcnt lgkmcnt(0)
	v_add_f32_e32 v132, v132, v133
	ds_bpermute_b32 v133, v182, v132
	s_waitcnt lgkmcnt(0)
	v_add_f32_e32 v132, v132, v133
	v_fmac_f32_e32 v65, 0xb9800000, v132
	v_fmac_f32_e32 v64, 0xb9800000, v132
	v_fmac_f32_e32 v67, 0xb9800000, v132
	v_fmac_f32_e32 v66, 0xb9800000, v132
	v_fmac_f32_e32 v41, 0xb9800000, v132
	v_fmac_f32_e32 v40, 0xb9800000, v132
	v_fmac_f32_e32 v43, 0xb9800000, v132
	v_fmac_f32_e32 v42, 0xb9800000, v132
	v_fmac_f32_e32 v45, 0xb9800000, v132
	v_fmac_f32_e32 v44, 0xb9800000, v132
	v_fmac_f32_e32 v47, 0xb9800000, v132
	v_fmac_f32_e32 v46, 0xb9800000, v132
	v_fmac_f32_e32 v51, 0xb9800000, v132
	v_fmac_f32_e32 v50, 0xb9800000, v132
	v_fmac_f32_e32 v49, 0xb9800000, v132
	v_fmac_f32_e32 v48, 0xb9800000, v132
	v_fmac_f32_e32 v53, 0xb9800000, v132
	v_fmac_f32_e32 v52, 0xb9800000, v132
	v_fmac_f32_e32 v55, 0xb9800000, v132
	v_fmac_f32_e32 v54, 0xb9800000, v132
	v_fmac_f32_e32 v57, 0xb9800000, v132
	v_fmac_f32_e32 v56, 0xb9800000, v132
	v_fmac_f32_e32 v59, 0xb9800000, v132
	v_fmac_f32_e32 v58, 0xb9800000, v132
	v_fmac_f32_e32 v63, 0xb9800000, v132
	v_fmac_f32_e32 v62, 0xb9800000, v132
	v_fmac_f32_e32 v61, 0xb9800000, v132
	v_fmac_f32_e32 v60, 0xb9800000, v132
	v_fmac_f32_e32 v69, 0xb9800000, v132
	v_fmac_f32_e32 v68, 0xb9800000, v132
	v_fmac_f32_e32 v71, 0xb9800000, v132
	v_fmac_f32_e32 v70, 0xb9800000, v132
	v_fmac_f32_e32 v73, 0xb9800000, v132
	v_fmac_f32_e32 v72, 0xb9800000, v132
	v_fmac_f32_e32 v75, 0xb9800000, v132
	v_fmac_f32_e32 v74, 0xb9800000, v132
	v_fmac_f32_e32 v79, 0xb9800000, v132
	v_fmac_f32_e32 v78, 0xb9800000, v132
	v_fmac_f32_e32 v77, 0xb9800000, v132
	v_fmac_f32_e32 v76, 0xb9800000, v132
	v_fmac_f32_e32 v81, 0xb9800000, v132
	v_fmac_f32_e32 v80, 0xb9800000, v132
	v_fmac_f32_e32 v83, 0xb9800000, v132
	v_fmac_f32_e32 v82, 0xb9800000, v132
	v_fmac_f32_e32 v85, 0xb9800000, v132
	v_fmac_f32_e32 v84, 0xb9800000, v132
	v_fmac_f32_e32 v87, 0xb9800000, v132
	v_fmac_f32_e32 v86, 0xb9800000, v132
	v_fmac_f32_e32 v91, 0xb9800000, v132
	v_fmac_f32_e32 v90, 0xb9800000, v132
	v_fmac_f32_e32 v89, 0xb9800000, v132
	v_fmac_f32_e32 v88, 0xb9800000, v132
	v_fmac_f32_e32 v93, 0xb9800000, v132
	v_fmac_f32_e32 v92, 0xb9800000, v132
	v_fmac_f32_e32 v95, 0xb9800000, v132
	v_fmac_f32_e32 v94, 0xb9800000, v132
	v_fmac_f32_e32 v97, 0xb9800000, v132
	v_fmac_f32_e32 v96, 0xb9800000, v132
	v_fmac_f32_e32 v99, 0xb9800000, v132
	v_fmac_f32_e32 v98, 0xb9800000, v132
	v_fmac_f32_e32 v103, 0xb9800000, v132
	v_fmac_f32_e32 v102, 0xb9800000, v132
	v_fmac_f32_e32 v101, 0xb9800000, v132
	v_fmac_f32_e32 v100, 0xb9800000, v132
	v_pk_mul_f32 v[132:133], v[66:67], v[66:67]
	v_pk_mul_f32 v[134:135], v[64:65], v[64:65]
	v_pk_mul_f32 v[136:137], v[42:43], v[42:43]
	v_pk_mul_f32 v[138:139], v[40:41], v[40:41]
	v_pk_mov_b32 v[176:177], v[134:135], v[132:133] op_sel:[1,0]
	v_mov_b32_e32 v135, v133
	v_pk_mov_b32 v[132:133], v[138:139], v[136:137] op_sel:[1,0]
	v_mov_b32_e32 v139, v137
	v_mul_f32_e32 v140, v44, v44
	v_mul_f32_e32 v142, v46, v46
	v_pk_add_f32 v[134:135], v[176:177], v[134:135]
	v_pk_add_f32 v[132:133], v[132:133], v[138:139]
	v_pk_fma_f32 v[136:137], v[44:45], v[44:45], v[140:141] op_sel_hi:[1,1,0]
	v_pk_fma_f32 v[140:141], v[46:47], v[46:47], v[142:143] op_sel_hi:[1,1,0]
	v_pk_add_f32 v[134:135], v[134:135], v[134:135] op_sel_hi:[0,1]
	v_pk_add_f32 v[132:133], v[132:133], v[132:133] op_sel_hi:[0,1]
	v_pk_mul_f32 v[144:145], v[54:55], v[54:55]
	v_pk_mul_f32 v[146:147], v[52:53], v[52:53]
	v_mul_f32_e32 v136, v48, v48
	v_mul_f32_e32 v140, v49, v49
	v_mul_f32_e32 v134, v50, v50
	v_mul_f32_e32 v132, v51, v51
	v_pk_mov_b32 v[142:143], v[146:147], v[144:145] op_sel:[1,0]
	v_mov_b32_e32 v147, v145
	v_pk_add_f32 v[136:137], v[136:137], v[140:141]
	v_pk_add_f32 v[132:133], v[134:135], v[132:133]
	v_mul_f32_e32 v148, v56, v56
	v_mul_f32_e32 v150, v58, v58
	v_pk_add_f32 v[138:139], v[142:143], v[146:147]
	v_pk_add_f32 v[132:133], v[136:137], v[132:133]
	v_pk_fma_f32 v[144:145], v[56:57], v[56:57], v[148:149] op_sel_hi:[1,1,0]
	v_pk_fma_f32 v[148:149], v[58:59], v[58:59], v[150:151] op_sel_hi:[1,1,0]
	v_pk_add_f32 v[138:139], v[138:139], v[138:139] op_sel_hi:[0,1]
	v_pk_add_f32 v[132:133], v[132:133], v[132:133] op_sel_hi:[0,1]
	v_pk_mul_f32 v[152:153], v[70:71], v[70:71]
	v_pk_mul_f32 v[154:155], v[68:69], v[68:69]
	v_mul_f32_e32 v144, v60, v60
	v_mul_f32_e32 v148, v61, v61
	v_mul_f32_e32 v138, v62, v62
	v_mul_f32_e32 v132, v63, v63
	v_pk_mov_b32 v[150:151], v[154:155], v[152:153] op_sel:[1,0]
	v_mov_b32_e32 v155, v153
	v_pk_add_f32 v[140:141], v[144:145], v[148:149]
	v_pk_add_f32 v[132:133], v[138:139], v[132:133]
	v_mul_f32_e32 v156, v72, v72
	v_mul_f32_e32 v158, v74, v74
	v_pk_add_f32 v[142:143], v[150:151], v[154:155]
	v_pk_add_f32 v[132:133], v[140:141], v[132:133]
	v_pk_fma_f32 v[152:153], v[72:73], v[72:73], v[156:157] op_sel_hi:[1,1,0]
	v_pk_fma_f32 v[156:157], v[74:75], v[74:75], v[158:159] op_sel_hi:[1,1,0]
	v_pk_add_f32 v[142:143], v[142:143], v[142:143] op_sel_hi:[0,1]
	v_pk_add_f32 v[132:133], v[132:133], v[132:133] op_sel_hi:[0,1]
	v_pk_mul_f32 v[160:161], v[82:83], v[82:83]
	v_pk_mul_f32 v[162:163], v[80:81], v[80:81]
	v_mul_f32_e32 v152, v76, v76
	v_mul_f32_e32 v156, v77, v77
	v_mul_f32_e32 v142, v78, v78
	v_mul_f32_e32 v132, v79, v79
	v_pk_mov_b32 v[158:159], v[162:163], v[160:161] op_sel:[1,0]
	v_mov_b32_e32 v163, v161
	v_pk_add_f32 v[144:145], v[152:153], v[156:157]
	v_pk_add_f32 v[132:133], v[142:143], v[132:133]
	v_mul_f32_e32 v164, v84, v84
	v_mul_f32_e32 v166, v86, v86
	v_pk_add_f32 v[146:147], v[158:159], v[162:163]
	v_pk_add_f32 v[132:133], v[144:145], v[132:133]
	v_pk_fma_f32 v[160:161], v[84:85], v[84:85], v[164:165] op_sel_hi:[1,1,0]
	v_pk_fma_f32 v[164:165], v[86:87], v[86:87], v[166:167] op_sel_hi:[1,1,0]
	v_pk_add_f32 v[146:147], v[146:147], v[146:147] op_sel_hi:[0,1]
	v_pk_add_f32 v[132:133], v[132:133], v[132:133] op_sel_hi:[0,1]
	v_pk_mul_f32 v[168:169], v[94:95], v[94:95]
	v_pk_mul_f32 v[170:171], v[92:93], v[92:93]
	v_mul_f32_e32 v160, v88, v88
	v_mul_f32_e32 v164, v89, v89
	v_mul_f32_e32 v146, v90, v90
	v_mul_f32_e32 v132, v91, v91
	v_pk_mov_b32 v[166:167], v[170:171], v[168:169] op_sel:[1,0]
	v_mov_b32_e32 v171, v169
	v_pk_add_f32 v[148:149], v[160:161], v[164:165]
	v_pk_add_f32 v[132:133], v[146:147], v[132:133]
	v_mul_f32_e32 v172, v96, v96
	v_mul_f32_e32 v174, v98, v98
	v_pk_add_f32 v[150:151], v[166:167], v[170:171]
	v_pk_add_f32 v[132:133], v[148:149], v[132:133]
	v_pk_fma_f32 v[168:169], v[96:97], v[96:97], v[172:173] op_sel_hi:[1,1,0]
	v_pk_fma_f32 v[172:173], v[98:99], v[98:99], v[174:175] op_sel_hi:[1,1,0]
	v_pk_add_f32 v[150:151], v[150:151], v[150:151] op_sel_hi:[0,1]
	v_pk_add_f32 v[132:133], v[132:133], v[132:133] op_sel_hi:[0,1]
	v_mul_f32_e32 v168, v100, v100
	v_mul_f32_e32 v172, v101, v101
	v_mul_f32_e32 v150, v102, v102
	v_mul_f32_e32 v132, v103, v103
	v_pk_add_f32 v[152:153], v[168:169], v[172:173]
	v_pk_add_f32 v[132:133], v[150:151], v[132:133]
	s_nop 0
	v_pk_add_f32 v[132:133], v[152:153], v[132:133]
	s_nop 0
	v_add_f32_e32 v132, v132, v133
	ds_bpermute_b32 v131, v131, v132
	s_waitcnt lgkmcnt(0)
	v_add_f32_e32 v131, v132, v131
	ds_bpermute_b32 v132, v178, v131
	s_waitcnt lgkmcnt(0)
	v_add_f32_e32 v131, v131, v132
	ds_bpermute_b32 v132, v179, v131
	s_waitcnt lgkmcnt(0)
	v_add_f32_e32 v131, v131, v132
	ds_bpermute_b32 v132, v180, v131
	s_waitcnt lgkmcnt(0)
	v_add_f32_e32 v131, v131, v132
	ds_bpermute_b32 v132, v181, v131
	s_waitcnt lgkmcnt(0)
	v_add_f32_e32 v131, v131, v132
	ds_bpermute_b32 v132, v182, v131
	s_waitcnt lgkmcnt(0)
	v_add_f32_e32 v131, v131, v132
	v_fmamk_f32 v131, v131, 0x39800000, v112
	v_mul_f32_e32 v132, 0x4f800000, v131
	v_cmp_gt_f32_e32 vcc, s24, v131
	s_nop 1
	v_cndmask_b32_e32 v131, v131, v132, vcc
	v_sqrt_f32_e32 v132, v131
	s_nop 0
	v_add_u32_e32 v133, -1, v132
	v_add_u32_e32 v134, 1, v132
	v_fma_f32 v135, -v133, v132, v131
	v_fma_f32 v136, -v134, v132, v131
	v_cmp_ge_f32_e64 s[4:5], 0, v135
	s_nop 1
	v_cndmask_b32_e64 v132, v132, v133, s[4:5]
	v_cmp_lt_f32_e64 s[4:5], 0, v136
	s_nop 1
	v_cndmask_b32_e64 v132, v132, v134, s[4:5]
	v_mul_f32_e32 v133, 0x37800000, v132
	v_cndmask_b32_e32 v132, v132, v133, vcc
	v_cmp_class_f32_e32 vcc, v131, v113
	s_nop 1
	v_cndmask_b32_e32 v131, v132, v131, vcc
	v_div_scale_f32 v132, s[4:5], v131, v131, 1.0
	v_rcp_f32_e32 v134, v132
	v_div_scale_f32 v133, vcc, 1.0, v131, 1.0
	v_fma_f32 v135, -v132, v134, 1.0
	v_fmac_f32_e32 v134, v135, v134
	v_mul_f32_e32 v135, v133, v134
	v_fma_f32 v136, -v132, v135, v133
	v_fmac_f32_e32 v135, v136, v134
	v_fma_f32 v132, -v132, v135, v133
	v_div_fmas_f32 v132, v132, v134, v135
	v_div_fixup_f32 v132, v132, v131, 1.0
	v_pk_mul_f32 v[64:65], v[64:65], v[132:133] op_sel_hi:[1,0]
	v_pk_mul_f32 v[40:41], v[40:41], v[132:133] op_sel_hi:[1,0]
	v_pk_fma_f32 v[10:11], v[10:11], v[64:65], v[26:27]
	v_pk_fma_f32 v[2:3], v[2:3], v[40:41], v[18:19]
	v_cvt_pk_fp8_f32 v115, v10, v11
	v_pk_mul_f32 v[66:67], v[66:67], v[132:133] op_sel_hi:[1,0]
	v_pk_mul_f32 v[44:45], v[44:45], v[132:133] op_sel_hi:[1,0]
	v_pk_mul_f32 v[48:49], v[48:49], v[132:133] op_sel_hi:[1,0]
	v_cvt_pk_fp8_f32 v116, v2, v3
	v_pk_fma_f32 v[12:13], v[12:13], v[66:67], v[28:29]
	v_pk_fma_f32 v[14:15], v[14:15], v[44:45], v[30:31]
	v_pk_fma_f32 v[6:7], v[6:7], v[48:49], v[22:23]
	v_pk_mul_f32 v[42:43], v[42:43], v[132:133] op_sel_hi:[1,0]
	v_cvt_pk_fp8_f32 v117, v14, v15
	v_cvt_pk_fp8_f32 v119, v6, v7
	v_cvt_pk_fp8_f32 v115, v12, v13 op_sel:[0,0,1]
	v_pk_fma_f32 v[4:5], v[4:5], v[42:43], v[20:21]
	v_pk_mul_f32 v[46:47], v[46:47], v[132:133] op_sel_hi:[1,0]
	v_pk_mul_f32 v[50:51], v[50:51], v[132:133] op_sel_hi:[1,0]
	v_cvt_pk_fp8_f32 v116, v4, v5 op_sel:[0,0,1]
	v_pk_fma_f32 v[16:17], v[16:17], v[46:47], v[32:33]
	v_pk_fma_f32 v[8:9], v[8:9], v[50:51], v[24:25]
	v_cvt_pk_f16_f32 v19, v12, v13
	v_cvt_pk_f16_f32 v18, v10, v11
	v_cvt_pk_f16_f32 v11, v4, v5
	v_cvt_pk_f16_f32 v10, v2, v3
	v_cvt_pk_f16_f32 v3, v16, v17
	v_cvt_pk_f16_f32 v2, v14, v15
	v_cvt_pk_f16_f32 v15, v8, v9
	v_cvt_pk_f16_f32 v14, v6, v7
	global_store_dwordx2 v34, v[18:19], s[14:15] nt
	v_cvt_pk_fp8_f32 v117, v16, v17 op_sel:[0,0,1]
	v_cvt_pk_fp8_f32 v119, v8, v9 op_sel:[0,0,1]
	global_store_dword v114, v115, s[10:11] nt
	global_store_dwordx2 v34, v[10:11], s[14:15] offset:512 nt
	global_store_dword v114, v116, s[10:11] offset:256 nt
	global_store_dwordx2 v34, v[2:3], s[14:15] offset:1024 nt
	global_store_dword v114, v117, s[10:11] offset:512 nt
	global_store_dwordx2 v34, v[14:15], s[14:15] offset:1536 nt
	global_store_dword v114, v119, s[10:11] offset:768 nt
	v_pk_mul_f32 v[52:53], v[52:53], v[132:133] op_sel_hi:[1,0]
	ds_read_b128 v[2:5], v1 offset:4096
	ds_read_b128 v[6:9], v1 offset:5120
	ds_read_b128 v[10:13], v1 offset:20480
	ds_read_b128 v[14:17], v1 offset:21504
	ds_read_b128 v[18:21], v1 offset:6144
	ds_read_b128 v[22:25], v1 offset:7168
	ds_read_b128 v[26:29], v1 offset:22528
	ds_read_b128 v[30:33], v1 offset:23552
	s_waitcnt lgkmcnt(5)
	v_pk_fma_f32 v[2:3], v[2:3], v[52:53], v[10:11]
	v_pk_mul_f32 v[56:57], v[56:57], v[132:133] op_sel_hi:[1,0]
	v_cvt_pk_fp8_f32 v118, v2, v3
	s_waitcnt lgkmcnt(4)
	v_pk_fma_f32 v[6:7], v[6:7], v[56:57], v[14:15]
	v_pk_mul_f32 v[54:55], v[54:55], v[132:133] op_sel_hi:[1,0]
	v_pk_mul_f32 v[58:59], v[58:59], v[132:133] op_sel_hi:[1,0]
	v_pk_mul_f32 v[60:61], v[60:61], v[132:133] op_sel_hi:[1,0]
	v_pk_mul_f32 v[68:69], v[68:69], v[132:133] op_sel_hi:[1,0]
	v_cvt_pk_fp8_f32 v120, v6, v7
	v_pk_fma_f32 v[4:5], v[4:5], v[54:55], v[12:13]
	v_pk_fma_f32 v[8:9], v[8:9], v[58:59], v[16:17]
	s_waitcnt lgkmcnt(1)
	v_pk_fma_f32 v[12:13], v[60:61], v[18:19], v[26:27]
	s_waitcnt lgkmcnt(0)
	v_pk_fma_f32 v[16:17], v[68:69], v[22:23], v[30:31]
	v_cvt_pk_fp8_f32 v121, v12, v13
	v_cvt_pk_fp8_f32 v123, v16, v17
	v_cvt_pk_fp8_f32 v118, v4, v5 op_sel:[0,0,1]
	v_pk_mul_f32 v[62:63], v[62:63], v[132:133] op_sel_hi:[1,0]
	v_pk_mul_f32 v[70:71], v[70:71], v[132:133] op_sel_hi:[1,0]
	v_cvt_pk_fp8_f32 v120, v8, v9 op_sel:[0,0,1]
	v_pk_fma_f32 v[10:11], v[62:63], v[20:21], v[28:29]
	v_pk_fma_f32 v[14:15], v[70:71], v[24:25], v[32:33]
	v_cvt_pk_f16_f32 v18, v2, v3
	v_cvt_pk_f16_f32 v19, v4, v5
	v_cvt_pk_f16_f32 v2, v6, v7
	v_cvt_pk_f16_f32 v3, v8, v9
	v_cvt_pk_f16_f32 v6, v12, v13
	v_cvt_pk_f16_f32 v7, v10, v11
	v_cvt_pk_f16_f32 v12, v16, v17
	v_cvt_pk_f16_f32 v13, v14, v15
	global_store_dwordx2 v34, v[18:19], s[14:15] offset:2048 nt
	v_cvt_pk_fp8_f32 v121, v10, v11 op_sel:[0,0,1]
	v_cvt_pk_fp8_f32 v123, v14, v15 op_sel:[0,0,1]
	global_store_dword v114, v118, s[10:11] offset:1024 nt
	global_store_dwordx2 v34, v[2:3], s[14:15] offset:2560 nt
	global_store_dword v114, v120, s[10:11] offset:1280 nt
	global_store_dwordx2 v34, v[6:7], s[14:15] offset:3072 nt
	global_store_dword v114, v121, s[10:11] offset:1536 nt
	global_store_dwordx2 v34, v[12:13], s[14:15] offset:3584 nt
	global_store_dword v114, v123, s[10:11] offset:1792 nt
	v_pk_mul_f32 v[72:73], v[72:73], v[132:133] op_sel_hi:[1,0]
	ds_read_b128 v[2:5], v1 offset:8192
	ds_read_b128 v[6:9], v1 offset:9216
	ds_read_b128 v[10:13], v1 offset:24576
	ds_read_b128 v[14:17], v1 offset:25600
	ds_read_b128 v[18:21], v1 offset:10240
	ds_read_b128 v[22:25], v1 offset:11264
	ds_read_b128 v[26:29], v1 offset:26624
	ds_read_b128 v[30:33], v1 offset:27648
	s_waitcnt lgkmcnt(5)
	v_pk_fma_f32 v[2:3], v[72:73], v[2:3], v[10:11]
	v_pk_mul_f32 v[76:77], v[76:77], v[132:133] op_sel_hi:[1,0]
	v_cvt_pk_fp8_f32 v122, v2, v3
	s_waitcnt lgkmcnt(4)
	v_pk_fma_f32 v[6:7], v[76:77], v[6:7], v[14:15]
	v_pk_mul_f32 v[74:75], v[74:75], v[132:133] op_sel_hi:[1,0]
	v_pk_mul_f32 v[78:79], v[78:79], v[132:133] op_sel_hi:[1,0]
	v_pk_mul_f32 v[80:81], v[80:81], v[132:133] op_sel_hi:[1,0]
	v_pk_mul_f32 v[84:85], v[84:85], v[132:133] op_sel_hi:[1,0]
	v_cvt_pk_fp8_f32 v124, v6, v7
	v_pk_fma_f32 v[4:5], v[74:75], v[4:5], v[12:13]
	v_pk_fma_f32 v[8:9], v[78:79], v[8:9], v[16:17]
	s_waitcnt lgkmcnt(1)
	v_pk_fma_f32 v[12:13], v[80:81], v[18:19], v[26:27]
	s_waitcnt lgkmcnt(0)
	v_pk_fma_f32 v[16:17], v[84:85], v[22:23], v[30:31]
	v_cvt_pk_fp8_f32 v125, v12, v13
	v_cvt_pk_fp8_f32 v127, v16, v17
	v_cvt_pk_fp8_f32 v122, v4, v5 op_sel:[0,0,1]
	v_pk_mul_f32 v[82:83], v[82:83], v[132:133] op_sel_hi:[1,0]
	v_pk_mul_f32 v[86:87], v[86:87], v[132:133] op_sel_hi:[1,0]
	v_cvt_pk_fp8_f32 v124, v8, v9 op_sel:[0,0,1]
	v_pk_fma_f32 v[10:11], v[82:83], v[20:21], v[28:29]
	v_pk_fma_f32 v[14:15], v[86:87], v[24:25], v[32:33]
	v_cvt_pk_f16_f32 v18, v2, v3
	v_cvt_pk_f16_f32 v19, v4, v5
	v_cvt_pk_f16_f32 v2, v6, v7
	v_cvt_pk_f16_f32 v3, v8, v9
	v_cvt_pk_f16_f32 v6, v12, v13
	v_cvt_pk_f16_f32 v7, v10, v11
	v_cvt_pk_f16_f32 v12, v16, v17
	v_cvt_pk_f16_f32 v13, v14, v15
	global_store_dwordx2 v[38:39], v[18:19], off nt
	v_cvt_pk_fp8_f32 v125, v10, v11 op_sel:[0,0,1]
	v_cvt_pk_fp8_f32 v127, v14, v15 op_sel:[0,0,1]
	global_store_dword v114, v122, s[10:11] offset:2048 nt
	global_store_dwordx2 v[38:39], v[2:3], off offset:512 nt
	global_store_dword v114, v124, s[10:11] offset:2304 nt
	global_store_dwordx2 v[38:39], v[6:7], off offset:1024 nt
	global_store_dword v114, v125, s[10:11] offset:2560 nt
	global_store_dwordx2 v[38:39], v[12:13], off offset:1536 nt
	global_store_dword v114, v127, s[10:11] offset:2816 nt
	v_pk_mul_f32 v[88:89], v[88:89], v[132:133] op_sel_hi:[1,0]
	ds_read_b128 v[2:5], v1 offset:12288
	ds_read_b128 v[6:9], v1 offset:13312
	ds_read_b128 v[10:13], v1 offset:28672
	ds_read_b128 v[14:17], v1 offset:29696
	ds_read_b128 v[18:21], v1 offset:14336
	ds_read_b128 v[22:25], v1 offset:15360
	ds_read_b128 v[26:29], v1 offset:30720
	ds_read_b128 v[30:33], v1 offset:31744
	s_waitcnt lgkmcnt(5)
	v_pk_fma_f32 v[2:3], v[88:89], v[2:3], v[10:11]
	v_pk_mul_f32 v[92:93], v[92:93], v[132:133] op_sel_hi:[1,0]
	v_cvt_pk_fp8_f32 v126, v2, v3
	s_waitcnt lgkmcnt(4)
	v_pk_fma_f32 v[6:7], v[92:93], v[6:7], v[14:15]
	v_pk_mul_f32 v[90:91], v[90:91], v[132:133] op_sel_hi:[1,0]
	v_pk_mul_f32 v[94:95], v[94:95], v[132:133] op_sel_hi:[1,0]
	v_pk_mul_f32 v[96:97], v[96:97], v[132:133] op_sel_hi:[1,0]
	v_pk_mul_f32 v[100:101], v[100:101], v[132:133] op_sel_hi:[1,0]
	v_cvt_pk_fp8_f32 v128, v6, v7
	v_pk_fma_f32 v[4:5], v[90:91], v[4:5], v[12:13]
	v_pk_fma_f32 v[8:9], v[94:95], v[8:9], v[16:17]
	s_waitcnt lgkmcnt(1)
	v_pk_fma_f32 v[12:13], v[96:97], v[18:19], v[26:27]
	s_waitcnt lgkmcnt(0)
	v_pk_fma_f32 v[16:17], v[100:101], v[22:23], v[30:31]
	v_cvt_pk_fp8_f32 v129, v12, v13
	v_cvt_pk_fp8_f32 v130, v16, v17
	v_cvt_pk_fp8_f32 v126, v4, v5 op_sel:[0,0,1]
	v_pk_mul_f32 v[98:99], v[98:99], v[132:133] op_sel_hi:[1,0]
	v_pk_mul_f32 v[102:103], v[102:103], v[132:133] op_sel_hi:[1,0]
	v_cvt_pk_fp8_f32 v128, v8, v9 op_sel:[0,0,1]
	v_pk_fma_f32 v[10:11], v[98:99], v[20:21], v[28:29]
	v_pk_fma_f32 v[14:15], v[102:103], v[24:25], v[32:33]
	v_cvt_pk_f16_f32 v18, v2, v3
	v_cvt_pk_f16_f32 v19, v4, v5
	v_cvt_pk_f16_f32 v2, v6, v7
	v_cvt_pk_f16_f32 v3, v8, v9
	v_cvt_pk_f16_f32 v6, v12, v13
	v_cvt_pk_f16_f32 v7, v10, v11
	v_cvt_pk_f16_f32 v12, v16, v17
	v_cvt_pk_f16_f32 v13, v14, v15
	global_store_dwordx2 v[38:39], v[18:19], off offset:2048 nt
	v_cvt_pk_fp8_f32 v129, v10, v11 op_sel:[0,0,1]
	v_cvt_pk_fp8_f32 v130, v14, v15 op_sel:[0,0,1]
	global_store_dword v114, v126, s[10:11] offset:3072 nt
	global_store_dwordx2 v[38:39], v[2:3], off offset:2560 nt
	global_store_dword v114, v128, s[10:11] offset:3328 nt
	global_store_dwordx2 v[38:39], v[6:7], off offset:3072 nt
	global_store_dword v114, v129, s[10:11] offset:3584 nt
	global_store_dwordx2 v[38:39], v[12:13], off offset:3584 nt
	global_store_dword v114, v130, s[10:11] offset:3840 nt
	s_add_u32 s10, s10, s12
	s_addc_u32 s11, s11, s13
	s_add_u32 s14, s14, s16
	s_addc_u32 s15, s15, s17
	s_add_u32 s30, s30, s34
	s_addc_u32 s31, s31, s35
	s_cmpk_lt_i32 s6, 0x4000
	s_cbranch_scc1 .LBB0_838

.LBB0_1098:
	global_load_dwordx4 v[10:13], v[6:7], off nt
	global_load_dwordx4 v[14:17], v[4:5], off nt
	v_add_u32_e32 v1, 0x200, v1
	v_cmp_lt_i32_e32 vcc, s14, v1
	v_lshl_add_u64 v[4:5], v[4:5], 0, s[10:11]
	v_lshl_add_u64 v[6:7], v[6:7], 0, s[10:11]
	s_or_b64 s[8:9], vcc, s[8:9]
	s_waitcnt vmcnt(1)
	ds_write_b128 v8, v[10:13]
	s_waitcnt vmcnt(0)
	ds_write_b128 v8, v[14:17] offset:16384
	v_add_u32_e32 v8, 0x2000, v8
	s_andn2_b64 exec, exec, s[8:9]
	s_cbranch_execnz .LBB0_1098

.LBB0_1101:
	v_cmp_lt_i32_e32 vcc, v88, v87
	v_lshl_add_u64 v[2:3], v[12:13], 0, s[12:13]
	s_add_u32 s4, s6, s12
	v_cndmask_b32_e32 v4, v86, v88, vcc
	v_cmp_lt_i32_e32 vcc, v89, v87
	s_addc_u32 s5, s7, s13
	v_lshlrev_b32_e32 v139, 2, v4
	v_cndmask_b32_e32 v5, v86, v89, vcc
	v_cmp_lt_i32_e32 vcc, v90, v87
	v_lshlrev_b32_e32 v142, 2, v5
	s_add_i32 s8, s8, s10
	v_cndmask_b32_e32 v6, v86, v90, vcc
	v_cmp_lt_i32_e32 vcc, v91, v87
	v_lshlrev_b32_e32 v143, 2, v6
	s_add_u32 s6, s6, s14
	v_cndmask_b32_e32 v7, v86, v91, vcc
	v_cmp_lt_i32_e32 vcc, v92, v87
	v_lshlrev_b32_e32 v144, 2, v7
	s_addc_u32 s7, s7, s15
	v_cndmask_b32_e32 v8, v86, v92, vcc
	v_cmp_lt_i32_e32 vcc, v93, v87
	v_lshlrev_b32_e32 v145, 2, v8
	v_lshl_add_u64 v[12:13], v[12:13], 0, s[14:15]
	v_cndmask_b32_e32 v9, v86, v93, vcc
	v_add_co_u32_e32 v18, vcc, s19, v2
	v_lshlrev_b32_e32 v146, 2, v9
	s_nop 0
	v_addc_co_u32_e32 v19, vcc, 0, v3, vcc
	v_add_co_u32_e32 v14, vcc, s24, v2
	s_cmpk_lt_i32 s8, 0x4000
	s_nop 0
	v_addc_co_u32_e32 v15, vcc, 0, v3, vcc
	v_lshl_add_u64 v[2:3], s[4:5], 0, v[10:11]
	v_add_co_u32_e32 v8, vcc, 0x2b200000, v2
	v_lshl_add_u64 v[4:5], v[2:3], 0, s[16:17]
	s_nop 0
	v_addc_co_u32_e32 v9, vcc, 0, v3, vcc
	v_lshl_add_u64 v[6:7], v[2:3], 0, s[30:31]
	v_add_co_u32_e32 v32, vcc, s3, v2
	global_load_dwordx2 v[22:23], v[4:5], off offset:512 nt
	global_load_dwordx2 v[24:25], v[4:5], off offset:1024 nt
	global_load_dwordx2 v[26:27], v[4:5], off offset:1536 nt
	global_load_dwordx2 v[28:29], v[4:5], off offset:2048 nt
	global_load_dwordx2 v[30:31], v[4:5], off offset:2560 nt
	global_load_dwordx2 v[34:35], v[4:5], off offset:3072 nt
	global_load_dwordx2 v[36:37], v[4:5], off offset:3584 nt
	global_load_dwordx2 v[38:39], v[6:7], off offset:512 nt
	global_load_dwordx2 v[40:41], v[6:7], off offset:1024 nt
	global_load_dwordx2 v[42:43], v[6:7], off offset:1536 nt
	global_load_dwordx2 v[44:45], v[6:7], off offset:2048 nt
	global_load_dwordx2 v[46:47], v[6:7], off offset:2560 nt
	global_load_dwordx2 v[48:49], v[6:7], off offset:3072 nt
	global_load_dwordx2 v[50:51], v[8:9], off nt
	v_addc_co_u32_e32 v33, vcc, 0, v3, vcc
	v_lshl_add_u64 v[20:21], v[2:3], 0, s[34:35]
	v_add_co_u32_e64 v16, s[4:5], s25, v2
	v_add_co_u32_e32 v2, vcc, s9, v2
	global_load_dwordx2 v[52:53], v[32:33], off offset:512 nt
	global_load_dwordx2 v[54:55], v[32:33], off offset:1024 nt
	global_load_dwordx2 v[56:57], v[32:33], off offset:1536 nt
	global_load_dwordx2 v[58:59], v[32:33], off offset:2048 nt
	v_addc_co_u32_e64 v17, s[4:5], 0, v3, s[4:5]
	v_addc_co_u32_e32 v3, vcc, 0, v3, vcc
	global_load_dwordx2 v[60:61], v[32:33], off nt
	global_load_dwordx2 v[62:63], v[6:7], off offset:3584 nt
	global_load_dwordx2 v[64:65], v[32:33], off offset:2560 nt
	global_load_dwordx2 v[66:67], v[32:33], off offset:3072 nt
	global_load_dwordx2 v[68:69], v[32:33], off offset:3584 nt
	global_load_dwordx2 v[70:71], v[2:3], off offset:-4096 nt
	global_load_dwordx2 v[72:73], v[2:3], off nt
	global_load_dwordx2 v[74:75], v[2:3], off offset:512 nt
	global_load_dwordx2 v[76:77], v[2:3], off offset:1024 nt
	global_load_dwordx2 v[78:79], v[2:3], off offset:1536 nt
	global_load_dwordx2 v[80:81], v[2:3], off offset:2048 nt
	global_load_dwordx2 v[82:83], v[2:3], off offset:2560 nt
	global_load_dwordx2 v[84:85], v[2:3], off offset:3072 nt
	global_load_dwordx2 v[96:97], v[2:3], off offset:3584 nt
	ds_read_b128 v[2:5], v1
	ds_read_b128 v[6:9], v1 offset:16384
	s_waitcnt vmcnt(26)
	v_lshlrev_b32_e32 v116, 16, v34
	v_lshlrev_b32_e32 v32, 16, v22
	v_and_b32_e32 v33, 0xffff0000, v22
	v_lshlrev_b32_e32 v98, 16, v23
	v_and_b32_e32 v99, 0xffff0000, v23
	v_lshlrev_b32_e32 v100, 16, v24
	v_and_b32_e32 v101, 0xffff0000, v24
	v_lshlrev_b32_e32 v102, 16, v25
	v_and_b32_e32 v103, 0xffff0000, v25
	v_lshlrev_b32_e32 v104, 16, v26
	v_and_b32_e32 v105, 0xffff0000, v26
	v_lshlrev_b32_e32 v106, 16, v27
	v_and_b32_e32 v107, 0xffff0000, v27
	v_lshlrev_b32_e32 v108, 16, v28
	v_and_b32_e32 v109, 0xffff0000, v28
	v_lshlrev_b32_e32 v110, 16, v29
	v_and_b32_e32 v111, 0xffff0000, v29
	v_lshlrev_b32_e32 v112, 16, v30
	v_and_b32_e32 v113, 0xffff0000, v30
	v_lshlrev_b32_e32 v114, 16, v31
	v_and_b32_e32 v115, 0xffff0000, v31
	v_and_b32_e32 v117, 0xffff0000, v34
	v_lshlrev_b32_e32 v118, 16, v35
	v_and_b32_e32 v119, 0xffff0000, v35
	s_waitcnt vmcnt(25)
	v_lshlrev_b32_e32 v120, 16, v36
	v_and_b32_e32 v121, 0xffff0000, v36
	v_lshlrev_b32_e32 v122, 16, v37
	v_and_b32_e32 v123, 0xffff0000, v37
	s_waitcnt vmcnt(18)
	v_lshlrev_b32_e32 v124, 16, v50
	v_and_b32_e32 v50, 0xffff0000, v50
	v_lshlrev_b32_e32 v125, 16, v51
	v_and_b32_e32 v51, 0xffff0000, v51
	v_fma_mix_f32 v22, v38, s11, v32 op_sel_hi:[1,0,0]
	v_fma_mix_f32 v23, v38, s11, v33 op_sel:[1,0,0] op_sel_hi:[1,0,0]
	v_fma_mix_f32 v24, v39, s11, v98 op_sel_hi:[1,0,0]
	v_fma_mix_f32 v25, v39, s11, v99 op_sel:[1,0,0] op_sel_hi:[1,0,0]
	v_fma_mix_f32 v26, v40, s11, v100 op_sel_hi:[1,0,0]
	v_fma_mix_f32 v27, v40, s11, v101 op_sel:[1,0,0] op_sel_hi:[1,0,0]
	v_fma_mix_f32 v28, v41, s11, v102 op_sel_hi:[1,0,0]
	v_fma_mix_f32 v29, v41, s11, v103 op_sel:[1,0,0] op_sel_hi:[1,0,0]
	v_fma_mix_f32 v30, v42, s11, v104 op_sel_hi:[1,0,0]
	v_fma_mix_f32 v31, v42, s11, v105 op_sel:[1,0,0] op_sel_hi:[1,0,0]
	v_fma_mix_f32 v32, v43, s11, v106 op_sel_hi:[1,0,0]
	v_fma_mix_f32 v33, v43, s11, v107 op_sel:[1,0,0] op_sel_hi:[1,0,0]
	v_fma_mix_f32 v34, v44, s11, v108 op_sel_hi:[1,0,0]
	v_fma_mix_f32 v35, v44, s11, v109 op_sel:[1,0,0] op_sel_hi:[1,0,0]
	v_fma_mix_f32 v36, v45, s11, v110 op_sel_hi:[1,0,0]
	v_fma_mix_f32 v37, v45, s11, v111 op_sel:[1,0,0] op_sel_hi:[1,0,0]
	v_fma_mix_f32 v38, v46, s11, v112 op_sel_hi:[1,0,0]
	v_fma_mix_f32 v39, v46, s11, v113 op_sel:[1,0,0] op_sel_hi:[1,0,0]
	v_fma_mix_f32 v40, v47, s11, v114 op_sel_hi:[1,0,0]
	v_fma_mix_f32 v41, v47, s11, v115 op_sel:[1,0,0] op_sel_hi:[1,0,0]
	v_fma_mix_f32 v42, v48, s11, v116 op_sel_hi:[1,0,0]
	v_fma_mix_f32 v43, v48, s11, v117 op_sel:[1,0,0] op_sel_hi:[1,0,0]
	v_fma_mix_f32 v44, v49, s11, v118 op_sel_hi:[1,0,0]
	v_fma_mix_f32 v45, v49, s11, v119 op_sel:[1,0,0] op_sel_hi:[1,0,0]
	s_waitcnt vmcnt(12)
	v_fma_mix_f32 v46, v62, s11, v120 op_sel_hi:[1,0,0]
	v_fma_mix_f32 v47, v62, s11, v121 op_sel:[1,0,0] op_sel_hi:[1,0,0]
	v_fma_mix_f32 v48, v63, s11, v122 op_sel_hi:[1,0,0]
	v_fma_mix_f32 v49, v63, s11, v123 op_sel:[1,0,0] op_sel_hi:[1,0,0]
	v_lshlrev_b32_e32 v62, 16, v60
	v_and_b32_e32 v63, 0xffff0000, v60
	v_lshlrev_b32_e32 v110, 16, v61
	v_and_b32_e32 v111, 0xffff0000, v61
	v_lshlrev_b32_e32 v112, 16, v52
	v_and_b32_e32 v113, 0xffff0000, v52
	v_lshlrev_b32_e32 v114, 16, v53
	v_and_b32_e32 v115, 0xffff0000, v53
	v_lshlrev_b32_e32 v116, 16, v54
	v_and_b32_e32 v117, 0xffff0000, v54
	v_lshlrev_b32_e32 v118, 16, v55
	v_and_b32_e32 v119, 0xffff0000, v55
	v_lshlrev_b32_e32 v120, 16, v56
	v_and_b32_e32 v121, 0xffff0000, v56
	v_lshlrev_b32_e32 v122, 16, v57
	v_and_b32_e32 v123, 0xffff0000, v57
	v_lshlrev_b32_e32 v126, 16, v58
	v_and_b32_e32 v127, 0xffff0000, v58
	v_lshlrev_b32_e32 v128, 16, v59
	v_and_b32_e32 v129, 0xffff0000, v59
	s_waitcnt vmcnt(11)
	v_lshlrev_b32_e32 v130, 16, v64
	v_and_b32_e32 v131, 0xffff0000, v64
	v_lshlrev_b32_e32 v132, 16, v65
	v_and_b32_e32 v133, 0xffff0000, v65
	s_waitcnt vmcnt(10)
	v_lshlrev_b32_e32 v134, 16, v66
	v_and_b32_e32 v135, 0xffff0000, v66
	v_lshlrev_b32_e32 v136, 16, v67
	v_and_b32_e32 v137, 0xffff0000, v67
	s_waitcnt vmcnt(9)
	v_lshlrev_b32_e32 v138, 16, v68
	v_and_b32_e32 v140, 0xffff0000, v68
	v_lshlrev_b32_e32 v141, 16, v69
	v_and_b32_e32 v147, 0xffff0000, v69
	s_waitcnt vmcnt(8)
	v_fma_mix_f32 v60, v70, s11, v124 op_sel_hi:[1,0,0]
	v_fma_mix_f32 v61, v70, s11, v50 op_sel:[1,0,0] op_sel_hi:[1,0,0]
	v_fma_mix_f32 v64, v71, s11, v125 op_sel_hi:[1,0,0]
	v_fma_mix_f32 v65, v71, s11, v51 op_sel:[1,0,0] op_sel_hi:[1,0,0]
	s_waitcnt vmcnt(7)
	v_fma_mix_f32 v50, v72, s11, v62 op_sel_hi:[1,0,0]
	v_fma_mix_f32 v51, v72, s11, v63 op_sel:[1,0,0] op_sel_hi:[1,0,0]
	v_fma_mix_f32 v52, v73, s11, v110 op_sel_hi:[1,0,0]
	v_fma_mix_f32 v53, v73, s11, v111 op_sel:[1,0,0] op_sel_hi:[1,0,0]
	s_waitcnt vmcnt(6)
	v_fma_mix_f32 v54, v74, s11, v112 op_sel_hi:[1,0,0]
	v_fma_mix_f32 v55, v74, s11, v113 op_sel:[1,0,0] op_sel_hi:[1,0,0]
	v_fma_mix_f32 v56, v75, s11, v114 op_sel_hi:[1,0,0]
	v_fma_mix_f32 v57, v75, s11, v115 op_sel:[1,0,0] op_sel_hi:[1,0,0]
	s_waitcnt vmcnt(5)
	v_fma_mix_f32 v58, v76, s11, v116 op_sel_hi:[1,0,0]
	v_fma_mix_f32 v59, v76, s11, v117 op_sel:[1,0,0] op_sel_hi:[1,0,0]
	v_fma_mix_f32 v62, v77, s11, v118 op_sel_hi:[1,0,0]
	v_fma_mix_f32 v63, v77, s11, v119 op_sel:[1,0,0] op_sel_hi:[1,0,0]
	s_waitcnt vmcnt(4)
	v_fma_mix_f32 v66, v78, s11, v120 op_sel_hi:[1,0,0]
	v_fma_mix_f32 v67, v78, s11, v121 op_sel:[1,0,0] op_sel_hi:[1,0,0]
	v_fma_mix_f32 v68, v79, s11, v122 op_sel_hi:[1,0,0]
	v_fma_mix_f32 v69, v79, s11, v123 op_sel:[1,0,0] op_sel_hi:[1,0,0]
	s_waitcnt vmcnt(3)
	v_fma_mix_f32 v70, v80, s11, v126 op_sel_hi:[1,0,0]
	v_fma_mix_f32 v71, v80, s11, v127 op_sel:[1,0,0] op_sel_hi:[1,0,0]
	v_fma_mix_f32 v72, v81, s11, v128 op_sel_hi:[1,0,0]
	v_fma_mix_f32 v73, v81, s11, v129 op_sel:[1,0,0] op_sel_hi:[1,0,0]
	s_waitcnt vmcnt(2)
	v_fma_mix_f32 v74, v82, s11, v130 op_sel_hi:[1,0,0]
	v_fma_mix_f32 v75, v82, s11, v131 op_sel:[1,0,0] op_sel_hi:[1,0,0]
	v_fma_mix_f32 v76, v83, s11, v132 op_sel_hi:[1,0,0]
	v_fma_mix_f32 v77, v83, s11, v133 op_sel:[1,0,0] op_sel_hi:[1,0,0]
	s_waitcnt vmcnt(1)
	v_fma_mix_f32 v78, v84, s11, v134 op_sel_hi:[1,0,0]
	v_fma_mix_f32 v79, v84, s11, v135 op_sel:[1,0,0] op_sel_hi:[1,0,0]
	v_fma_mix_f32 v80, v85, s11, v136 op_sel_hi:[1,0,0]
	v_fma_mix_f32 v81, v85, s11, v137 op_sel:[1,0,0] op_sel_hi:[1,0,0]
	s_waitcnt vmcnt(0)
	v_fma_mix_f32 v82, v96, s11, v138 op_sel_hi:[1,0,0]
	v_fma_mix_f32 v83, v96, s11, v140 op_sel:[1,0,0] op_sel_hi:[1,0,0]
	v_fma_mix_f32 v84, v97, s11, v141 op_sel_hi:[1,0,0]
	v_fma_mix_f32 v85, v97, s11, v147 op_sel:[1,0,0] op_sel_hi:[1,0,0]
	v_add_f32_e32 v96, v60, v61
	v_add_f32_e32 v97, v64, v65
	v_add_f32_e32 v98, v22, v23
	v_add_f32_e32 v99, v24, v25
	v_add_f32_e32 v96, v96, v97
	v_add_f32_e32 v100, v26, v27
	v_add_f32_e32 v101, v28, v29
	v_add_f32_e32 v98, v98, v99
	v_add_f32_e32 v96, 0, v96
	v_add_f32_e32 v102, v30, v31
	v_add_f32_e32 v103, v32, v33
	v_add_f32_e32 v99, v100, v101
	v_add_f32_e32 v96, v96, v98
	v_add_f32_e32 v104, v34, v35
	v_add_f32_e32 v105, v36, v37
	v_add_f32_e32 v100, v102, v103
	v_add_f32_e32 v96, v96, v99
	v_add_f32_e32 v106, v38, v39
	v_add_f32_e32 v107, v40, v41
	v_add_f32_e32 v101, v104, v105
	v_add_f32_e32 v96, v96, v100
	v_add_f32_e32 v108, v42, v43
	v_add_f32_e32 v109, v44, v45
	v_add_f32_e32 v102, v106, v107
	v_add_f32_e32 v96, v96, v101
	v_add_f32_e32 v103, v108, v109
	v_add_f32_e32 v104, v46, v47
	v_add_f32_e32 v105, v48, v49
	v_add_f32_e32 v96, v96, v102
	v_add_f32_e32 v104, v104, v105
	v_add_f32_e32 v105, v50, v51
	v_add_f32_e32 v106, v52, v53
	v_add_f32_e32 v96, v96, v103
	v_add_f32_e32 v107, v54, v55
	v_add_f32_e32 v108, v56, v57
	v_add_f32_e32 v97, v105, v106
	v_add_f32_e32 v96, v96, v104
	v_add_f32_e32 v109, v58, v59
	v_add_f32_e32 v110, v62, v63
	v_add_f32_e32 v105, v107, v108
	v_add_f32_e32 v96, v96, v97
	v_add_f32_e32 v111, v66, v67
	v_add_f32_e32 v112, v68, v69
	v_add_f32_e32 v106, v109, v110
	v_add_f32_e32 v96, v96, v105
	v_add_f32_e32 v113, v70, v71
	v_add_f32_e32 v114, v72, v73
	v_add_f32_e32 v107, v111, v112
	v_add_f32_e32 v96, v96, v106
	v_add_f32_e32 v115, v74, v75
	v_add_f32_e32 v116, v76, v77
	v_add_f32_e32 v108, v113, v114
	v_add_f32_e32 v96, v96, v107
	v_add_f32_e32 v117, v78, v79
	v_add_f32_e32 v118, v80, v81
	v_add_f32_e32 v109, v115, v116
	v_add_f32_e32 v96, v96, v108
	v_add_f32_e32 v119, v82, v83
	v_add_f32_e32 v120, v84, v85
	v_add_f32_e32 v110, v117, v118
	v_add_f32_e32 v96, v96, v109
	v_add_f32_e32 v111, v119, v120
	v_add_f32_e32 v96, v96, v110
	v_add_f32_e32 v96, v96, v111
	ds_bpermute_b32 v97, v139, v96
	s_waitcnt lgkmcnt(0)
	v_add_f32_e32 v96, v96, v97
	ds_bpermute_b32 v97, v142, v96
	s_waitcnt lgkmcnt(0)
	v_add_f32_e32 v96, v96, v97
	ds_bpermute_b32 v97, v143, v96
	s_waitcnt lgkmcnt(0)
	v_add_f32_e32 v96, v96, v97
	ds_bpermute_b32 v97, v144, v96
	s_waitcnt lgkmcnt(0)
	v_add_f32_e32 v96, v96, v97
	ds_bpermute_b32 v97, v145, v96
	s_waitcnt lgkmcnt(0)
	v_add_f32_e32 v96, v96, v97
	ds_bpermute_b32 v97, v146, v96
	s_waitcnt lgkmcnt(0)
	v_add_f32_e32 v96, v96, v97
	v_fmac_f32_e32 v61, 0xb9800000, v96
	v_fmac_f32_e32 v60, 0xb9800000, v96
	v_fmac_f32_e32 v65, 0xb9800000, v96
	v_fmac_f32_e32 v64, 0xb9800000, v96
	v_fmac_f32_e32 v23, 0xb9800000, v96
	v_fmac_f32_e32 v22, 0xb9800000, v96
	v_fmac_f32_e32 v25, 0xb9800000, v96
	v_fmac_f32_e32 v24, 0xb9800000, v96
	v_fmac_f32_e32 v27, 0xb9800000, v96
	v_fmac_f32_e32 v26, 0xb9800000, v96
	v_fmac_f32_e32 v29, 0xb9800000, v96
	v_fmac_f32_e32 v28, 0xb9800000, v96
	v_fmac_f32_e32 v33, 0xb9800000, v96
	v_fmac_f32_e32 v32, 0xb9800000, v96
	v_fmac_f32_e32 v31, 0xb9800000, v96
	v_fmac_f32_e32 v30, 0xb9800000, v96
	v_fmac_f32_e32 v35, 0xb9800000, v96
	v_fmac_f32_e32 v34, 0xb9800000, v96
	v_fmac_f32_e32 v37, 0xb9800000, v96
	v_fmac_f32_e32 v36, 0xb9800000, v96
	v_fmac_f32_e32 v39, 0xb9800000, v96
	v_fmac_f32_e32 v38, 0xb9800000, v96
	v_fmac_f32_e32 v41, 0xb9800000, v96
	v_fmac_f32_e32 v40, 0xb9800000, v96
	v_fmac_f32_e32 v45, 0xb9800000, v96
	v_fmac_f32_e32 v44, 0xb9800000, v96
	v_fmac_f32_e32 v43, 0xb9800000, v96
	v_fmac_f32_e32 v42, 0xb9800000, v96
	v_fmac_f32_e32 v47, 0xb9800000, v96
	v_fmac_f32_e32 v46, 0xb9800000, v96
	v_fmac_f32_e32 v49, 0xb9800000, v96
	v_fmac_f32_e32 v48, 0xb9800000, v96
	v_fmac_f32_e32 v51, 0xb9800000, v96
	v_fmac_f32_e32 v50, 0xb9800000, v96
	v_fmac_f32_e32 v53, 0xb9800000, v96
	v_fmac_f32_e32 v52, 0xb9800000, v96
	v_fmac_f32_e32 v57, 0xb9800000, v96
	v_fmac_f32_e32 v56, 0xb9800000, v96
	v_fmac_f32_e32 v55, 0xb9800000, v96
	v_fmac_f32_e32 v54, 0xb9800000, v96
	v_fmac_f32_e32 v59, 0xb9800000, v96
	v_fmac_f32_e32 v58, 0xb9800000, v96
	v_fmac_f32_e32 v63, 0xb9800000, v96
	v_fmac_f32_e32 v62, 0xb9800000, v96
	v_fmac_f32_e32 v67, 0xb9800000, v96
	v_fmac_f32_e32 v66, 0xb9800000, v96
	v_fmac_f32_e32 v69, 0xb9800000, v96
	v_fmac_f32_e32 v68, 0xb9800000, v96
	v_fmac_f32_e32 v73, 0xb9800000, v96
	v_fmac_f32_e32 v72, 0xb9800000, v96
	v_fmac_f32_e32 v71, 0xb9800000, v96
	v_fmac_f32_e32 v70, 0xb9800000, v96
	v_fmac_f32_e32 v75, 0xb9800000, v96
	v_fmac_f32_e32 v74, 0xb9800000, v96
	v_fmac_f32_e32 v77, 0xb9800000, v96
	v_fmac_f32_e32 v76, 0xb9800000, v96
	v_fmac_f32_e32 v79, 0xb9800000, v96
	v_fmac_f32_e32 v78, 0xb9800000, v96
	v_fmac_f32_e32 v81, 0xb9800000, v96
	v_fmac_f32_e32 v80, 0xb9800000, v96
	v_fmac_f32_e32 v85, 0xb9800000, v96
	v_fmac_f32_e32 v84, 0xb9800000, v96
	v_fmac_f32_e32 v83, 0xb9800000, v96
	v_fmac_f32_e32 v82, 0xb9800000, v96
	v_pk_mul_f32 v[96:97], v[64:65], v[64:65]
	v_pk_mul_f32 v[98:99], v[60:61], v[60:61]
	v_pk_mul_f32 v[100:101], v[24:25], v[24:25]
	v_pk_mul_f32 v[102:103], v[22:23], v[22:23]
	v_pk_mov_b32 v[140:141], v[98:99], v[96:97] op_sel:[1,0]
	v_mov_b32_e32 v99, v97
	v_pk_mov_b32 v[96:97], v[102:103], v[100:101] op_sel:[1,0]
	v_mov_b32_e32 v103, v101
	v_mul_f32_e32 v104, v26, v26
	v_mul_f32_e32 v106, v28, v28
	v_pk_add_f32 v[98:99], v[140:141], v[98:99]
	v_pk_add_f32 v[96:97], v[96:97], v[102:103]
	v_pk_fma_f32 v[100:101], v[26:27], v[26:27], v[104:105] op_sel_hi:[1,1,0]
	v_pk_fma_f32 v[104:105], v[28:29], v[28:29], v[106:107] op_sel_hi:[1,1,0]
	v_pk_add_f32 v[98:99], v[98:99], v[98:99] op_sel_hi:[0,1]
	v_pk_add_f32 v[96:97], v[96:97], v[96:97] op_sel_hi:[0,1]
	v_pk_mul_f32 v[108:109], v[36:37], v[36:37]
	v_pk_mul_f32 v[110:111], v[34:35], v[34:35]
	v_mul_f32_e32 v100, v30, v30
	v_mul_f32_e32 v104, v31, v31
	v_mul_f32_e32 v98, v32, v32
	v_mul_f32_e32 v96, v33, v33
	v_pk_mov_b32 v[106:107], v[110:111], v[108:109] op_sel:[1,0]
	v_mov_b32_e32 v111, v109
	v_pk_add_f32 v[100:101], v[100:101], v[104:105]
	v_pk_add_f32 v[96:97], v[98:99], v[96:97]
	v_mul_f32_e32 v112, v38, v38
	v_mul_f32_e32 v114, v40, v40
	v_pk_add_f32 v[102:103], v[106:107], v[110:111]
	v_pk_add_f32 v[96:97], v[100:101], v[96:97]
	v_pk_fma_f32 v[108:109], v[38:39], v[38:39], v[112:113] op_sel_hi:[1,1,0]
	v_pk_fma_f32 v[112:113], v[40:41], v[40:41], v[114:115] op_sel_hi:[1,1,0]
	v_pk_add_f32 v[102:103], v[102:103], v[102:103] op_sel_hi:[0,1]
	v_pk_add_f32 v[96:97], v[96:97], v[96:97] op_sel_hi:[0,1]
	v_pk_mul_f32 v[116:117], v[48:49], v[48:49]
	v_pk_mul_f32 v[118:119], v[46:47], v[46:47]
	v_mul_f32_e32 v108, v42, v42
	v_mul_f32_e32 v112, v43, v43
	v_mul_f32_e32 v102, v44, v44
	v_mul_f32_e32 v96, v45, v45
	v_pk_mov_b32 v[114:115], v[118:119], v[116:117] op_sel:[1,0]
	v_mov_b32_e32 v119, v117
	v_pk_add_f32 v[104:105], v[108:109], v[112:113]
	v_pk_add_f32 v[96:97], v[102:103], v[96:97]
	v_mul_f32_e32 v120, v50, v50
	v_mul_f32_e32 v122, v52, v52
	v_pk_add_f32 v[106:107], v[114:115], v[118:119]
	v_pk_add_f32 v[96:97], v[104:105], v[96:97]
	v_pk_fma_f32 v[116:117], v[50:51], v[50:51], v[120:121] op_sel_hi:[1,1,0]
	v_pk_fma_f32 v[120:121], v[52:53], v[52:53], v[122:123] op_sel_hi:[1,1,0]
	v_pk_add_f32 v[106:107], v[106:107], v[106:107] op_sel_hi:[0,1]
	v_pk_add_f32 v[96:97], v[96:97], v[96:97] op_sel_hi:[0,1]
	v_pk_mul_f32 v[124:125], v[62:63], v[62:63]
	v_pk_mul_f32 v[126:127], v[58:59], v[58:59]
	v_mul_f32_e32 v116, v54, v54
	v_mul_f32_e32 v120, v55, v55
	v_mul_f32_e32 v106, v56, v56
	v_mul_f32_e32 v96, v57, v57
	v_pk_mov_b32 v[122:123], v[126:127], v[124:125] op_sel:[1,0]
	v_mov_b32_e32 v127, v125
	v_pk_add_f32 v[108:109], v[116:117], v[120:121]
	v_pk_add_f32 v[96:97], v[106:107], v[96:97]
	v_mul_f32_e32 v128, v66, v66
	v_mul_f32_e32 v130, v68, v68
	v_pk_add_f32 v[110:111], v[122:123], v[126:127]
	v_pk_add_f32 v[96:97], v[108:109], v[96:97]
	v_pk_fma_f32 v[124:125], v[66:67], v[66:67], v[128:129] op_sel_hi:[1,1,0]
	v_pk_fma_f32 v[128:129], v[68:69], v[68:69], v[130:131] op_sel_hi:[1,1,0]
	v_pk_add_f32 v[110:111], v[110:111], v[110:111] op_sel_hi:[0,1]
	v_pk_add_f32 v[96:97], v[96:97], v[96:97] op_sel_hi:[0,1]
	v_pk_mul_f32 v[132:133], v[76:77], v[76:77]
	v_pk_mul_f32 v[134:135], v[74:75], v[74:75]
	v_mul_f32_e32 v124, v70, v70
	v_mul_f32_e32 v128, v71, v71
	v_mul_f32_e32 v110, v72, v72
	v_mul_f32_e32 v96, v73, v73
	v_pk_mov_b32 v[130:131], v[134:135], v[132:133] op_sel:[1,0]
	v_mov_b32_e32 v135, v133
	v_pk_add_f32 v[112:113], v[124:125], v[128:129]
	v_pk_add_f32 v[96:97], v[110:111], v[96:97]
	v_mul_f32_e32 v136, v78, v78
	v_mul_f32_e32 v138, v80, v80
	v_pk_add_f32 v[114:115], v[130:131], v[134:135]
	v_pk_add_f32 v[96:97], v[112:113], v[96:97]
	v_pk_fma_f32 v[132:133], v[78:79], v[78:79], v[136:137] op_sel_hi:[1,1,0]
	v_pk_fma_f32 v[136:137], v[80:81], v[80:81], v[138:139] op_sel_hi:[1,1,0]
	v_pk_add_f32 v[114:115], v[114:115], v[114:115] op_sel_hi:[0,1]
	v_pk_add_f32 v[96:97], v[96:97], v[96:97] op_sel_hi:[0,1]
	v_mul_f32_e32 v132, v82, v82
	v_mul_f32_e32 v136, v83, v83
	v_mul_f32_e32 v114, v84, v84
	v_mul_f32_e32 v96, v85, v85
	v_pk_add_f32 v[116:117], v[132:133], v[136:137]
	v_pk_add_f32 v[96:97], v[114:115], v[96:97]
	s_nop 0
	v_pk_add_f32 v[96:97], v[116:117], v[96:97]
	s_nop 0
	v_add_f32_e32 v96, v96, v97
	ds_bpermute_b32 v97, v139, v96
	s_waitcnt lgkmcnt(0)
	v_add_f32_e32 v96, v96, v97
	ds_bpermute_b32 v97, v142, v96
	s_waitcnt lgkmcnt(0)
	v_add_f32_e32 v96, v96, v97
	ds_bpermute_b32 v97, v143, v96
	s_waitcnt lgkmcnt(0)
	v_add_f32_e32 v96, v96, v97
	ds_bpermute_b32 v97, v144, v96
	s_waitcnt lgkmcnt(0)
	v_add_f32_e32 v96, v96, v97
	ds_bpermute_b32 v97, v145, v96
	s_waitcnt lgkmcnt(0)
	v_add_f32_e32 v96, v96, v97
	ds_bpermute_b32 v97, v146, v96
	s_waitcnt lgkmcnt(0)
	v_add_f32_e32 v96, v96, v97
	v_fmamk_f32 v96, v96, 0x39800000, v94
	v_mul_f32_e32 v97, 0x4f800000, v96
	v_cmp_gt_f32_e32 vcc, s18, v96
	s_nop 1
	v_cndmask_b32_e32 v96, v96, v97, vcc
	v_sqrt_f32_e32 v97, v96
	s_nop 0
	v_add_u32_e32 v98, -1, v97
	v_add_u32_e32 v99, 1, v97
	v_fma_f32 v100, -v98, v97, v96
	v_fma_f32 v101, -v99, v97, v96
	v_cmp_ge_f32_e64 s[4:5], 0, v100
	s_nop 1
	v_cndmask_b32_e64 v97, v97, v98, s[4:5]
	v_cmp_lt_f32_e64 s[4:5], 0, v101
	s_nop 1
	v_cndmask_b32_e64 v97, v97, v99, s[4:5]
	v_mul_f32_e32 v98, 0x37800000, v97
	v_cndmask_b32_e32 v97, v97, v98, vcc
	v_cmp_class_f32_e32 vcc, v96, v95
	s_nop 1
	v_cndmask_b32_e32 v96, v97, v96, vcc
	v_div_scale_f32 v97, s[4:5], v96, v96, 1.0
	v_rcp_f32_e32 v99, v97
	v_div_scale_f32 v98, vcc, 1.0, v96, 1.0
	v_fma_f32 v100, -v97, v99, 1.0
	v_fmac_f32_e32 v99, v100, v99
	v_mul_f32_e32 v100, v98, v99
	v_fma_f32 v101, -v97, v100, v98
	v_fmac_f32_e32 v100, v101, v99
	v_fma_f32 v97, -v97, v100, v98
	v_div_fmas_f32 v97, v97, v99, v100
	v_div_fixup_f32 v96, v97, v96, 1.0
	v_pk_mul_f32 v[60:61], v[60:61], v[96:97] op_sel_hi:[1,0]
	v_pk_mul_f32 v[64:65], v[64:65], v[96:97] op_sel_hi:[1,0]
	v_pk_fma_f32 v[2:3], v[2:3], v[60:61], v[6:7]
	v_pk_fma_f32 v[4:5], v[4:5], v[64:65], v[8:9]
	v_cvt_pk_f16_f32 v6, v2, v3
	v_cvt_pk_f16_f32 v7, v4, v5
	global_store_dwordx2 v[14:15], v[6:7], off offset:-4096 nt
	v_cvt_pk_bf16_f32 v60, v2, v3
	v_cvt_pk_bf16_f32 v61, v4, v5
	ds_read_b128 v[2:5], v1 offset:1024
	ds_read_b128 v[6:9], v1 offset:17408
	v_pk_mul_f32 v[22:23], v[22:23], v[96:97] op_sel_hi:[1,0]
	v_pk_mul_f32 v[24:25], v[24:25], v[96:97] op_sel_hi:[1,0]
	global_store_dwordx2 v[16:17], v[60:61], off offset:-4096 nt
	v_pk_mul_f32 v[26:27], v[26:27], v[96:97] op_sel_hi:[1,0]
	s_waitcnt lgkmcnt(0)
	v_pk_fma_f32 v[4:5], v[4:5], v[24:25], v[8:9]
	v_pk_fma_f32 v[2:3], v[2:3], v[22:23], v[6:7]
	v_cvt_pk_f16_f32 v7, v4, v5
	v_cvt_pk_f16_f32 v6, v2, v3
	global_store_dwordx2 v[18:19], v[6:7], off offset:512 nt
	v_cvt_pk_bf16_f32 v22, v2, v3
	v_cvt_pk_bf16_f32 v23, v4, v5
	ds_read_b128 v[2:5], v1 offset:2048
	ds_read_b128 v[6:9], v1 offset:18432
	v_pk_mul_f32 v[28:29], v[28:29], v[96:97] op_sel_hi:[1,0]
	global_store_dwordx2 v[20:21], v[22:23], off offset:512 nt
	v_pk_mul_f32 v[30:31], v[30:31], v[96:97] op_sel_hi:[1,0]
	v_pk_mul_f32 v[32:33], v[32:33], v[96:97] op_sel_hi:[1,0]
	s_waitcnt lgkmcnt(0)
	v_pk_fma_f32 v[4:5], v[4:5], v[28:29], v[8:9]
	v_pk_fma_f32 v[2:3], v[2:3], v[26:27], v[6:7]
	v_cvt_pk_f16_f32 v7, v4, v5
	v_cvt_pk_f16_f32 v6, v2, v3
	global_store_dwordx2 v[18:19], v[6:7], off offset:1024 nt
	v_cvt_pk_bf16_f32 v22, v2, v3
	v_cvt_pk_bf16_f32 v23, v4, v5
	ds_read_b128 v[2:5], v1 offset:3072
	ds_read_b128 v[6:9], v1 offset:19456
	global_store_dwordx2 v[20:21], v[22:23], off offset:1024 nt
	v_pk_mul_f32 v[34:35], v[34:35], v[96:97] op_sel_hi:[1,0]
	v_pk_mul_f32 v[36:37], v[36:37], v[96:97] op_sel_hi:[1,0]
	v_pk_mul_f32 v[38:39], v[38:39], v[96:97] op_sel_hi:[1,0]
	s_waitcnt lgkmcnt(0)
	v_pk_fma_f32 v[4:5], v[4:5], v[32:33], v[8:9]
	v_pk_fma_f32 v[2:3], v[2:3], v[30:31], v[6:7]
	v_cvt_pk_f16_f32 v7, v4, v5
	v_cvt_pk_f16_f32 v6, v2, v3
	global_store_dwordx2 v[18:19], v[6:7], off offset:1536 nt
	v_cvt_pk_bf16_f32 v2, v2, v3
	v_cvt_pk_bf16_f32 v3, v4, v5
	global_store_dwordx2 v[20:21], v[2:3], off offset:1536 nt
	ds_read_b128 v[2:5], v1 offset:4096
	ds_read_b128 v[6:9], v1 offset:20480
	v_pk_mul_f32 v[40:41], v[40:41], v[96:97] op_sel_hi:[1,0]
	v_pk_mul_f32 v[42:43], v[42:43], v[96:97] op_sel_hi:[1,0]
	v_pk_mul_f32 v[44:45], v[44:45], v[96:97] op_sel_hi:[1,0]
	v_pk_mul_f32 v[46:47], v[46:47], v[96:97] op_sel_hi:[1,0]
	s_waitcnt lgkmcnt(0)
	v_pk_fma_f32 v[4:5], v[4:5], v[36:37], v[8:9]
	v_pk_fma_f32 v[2:3], v[2:3], v[34:35], v[6:7]
	v_cvt_pk_f16_f32 v7, v4, v5
	v_cvt_pk_f16_f32 v6, v2, v3
	global_store_dwordx2 v[18:19], v[6:7], off offset:2048 nt
	v_cvt_pk_bf16_f32 v22, v2, v3
	v_cvt_pk_bf16_f32 v23, v4, v5
	ds_read_b128 v[2:5], v1 offset:5120
	ds_read_b128 v[6:9], v1 offset:21504
	global_store_dwordx2 v[20:21], v[22:23], off offset:2048 nt
	v_pk_mul_f32 v[48:49], v[48:49], v[96:97] op_sel_hi:[1,0]
	v_pk_mul_f32 v[50:51], v[50:51], v[96:97] op_sel_hi:[1,0]
	v_pk_mul_f32 v[52:53], v[52:53], v[96:97] op_sel_hi:[1,0]
	s_waitcnt lgkmcnt(0)
	v_pk_fma_f32 v[4:5], v[4:5], v[40:41], v[8:9]
	v_pk_fma_f32 v[2:3], v[2:3], v[38:39], v[6:7]
	v_cvt_pk_f16_f32 v7, v4, v5
	v_cvt_pk_f16_f32 v6, v2, v3
	global_store_dwordx2 v[18:19], v[6:7], off offset:2560 nt
	v_cvt_pk_bf16_f32 v22, v2, v3
	v_cvt_pk_bf16_f32 v23, v4, v5
	ds_read_b128 v[2:5], v1 offset:6144
	ds_read_b128 v[6:9], v1 offset:22528
	global_store_dwordx2 v[20:21], v[22:23], off offset:2560 nt
	v_pk_mul_f32 v[54:55], v[54:55], v[96:97] op_sel_hi:[1,0]
	v_pk_mul_f32 v[56:57], v[56:57], v[96:97] op_sel_hi:[1,0]
	v_pk_mul_f32 v[58:59], v[58:59], v[96:97] op_sel_hi:[1,0]
	s_waitcnt lgkmcnt(0)
	v_pk_fma_f32 v[4:5], v[44:45], v[4:5], v[8:9]
	v_pk_fma_f32 v[2:3], v[42:43], v[2:3], v[6:7]
	v_cvt_pk_f16_f32 v7, v4, v5
	v_cvt_pk_f16_f32 v6, v2, v3
	global_store_dwordx2 v[18:19], v[6:7], off offset:3072 nt
	v_cvt_pk_bf16_f32 v22, v2, v3
	v_cvt_pk_bf16_f32 v23, v4, v5
	ds_read_b128 v[2:5], v1 offset:7168
	ds_read_b128 v[6:9], v1 offset:23552
	global_store_dwordx2 v[20:21], v[22:23], off offset:3072 nt
	v_pk_mul_f32 v[62:63], v[62:63], v[96:97] op_sel_hi:[1,0]
	v_pk_mul_f32 v[66:67], v[66:67], v[96:97] op_sel_hi:[1,0]
	v_pk_mul_f32 v[68:69], v[68:69], v[96:97] op_sel_hi:[1,0]
	s_waitcnt lgkmcnt(0)
	v_pk_fma_f32 v[4:5], v[48:49], v[4:5], v[8:9]
	v_pk_fma_f32 v[2:3], v[46:47], v[2:3], v[6:7]
	v_cvt_pk_f16_f32 v7, v4, v5
	v_cvt_pk_f16_f32 v6, v2, v3
	global_store_dwordx2 v[18:19], v[6:7], off offset:3584 nt
	v_cvt_pk_bf16_f32 v2, v2, v3
	v_cvt_pk_bf16_f32 v3, v4, v5
	global_store_dwordx2 v[20:21], v[2:3], off offset:3584 nt
	ds_read_b128 v[2:5], v1 offset:8192
	ds_read_b128 v[6:9], v1 offset:24576
	v_pk_mul_f32 v[70:71], v[70:71], v[96:97] op_sel_hi:[1,0]
	v_pk_mul_f32 v[72:73], v[72:73], v[96:97] op_sel_hi:[1,0]
	v_pk_mul_f32 v[74:75], v[74:75], v[96:97] op_sel_hi:[1,0]
	v_pk_mul_f32 v[76:77], v[76:77], v[96:97] op_sel_hi:[1,0]
	s_waitcnt lgkmcnt(0)
	v_pk_fma_f32 v[4:5], v[52:53], v[4:5], v[8:9]
	v_pk_fma_f32 v[2:3], v[50:51], v[2:3], v[6:7]
	v_cvt_pk_f16_f32 v7, v4, v5
	v_cvt_pk_f16_f32 v6, v2, v3
	global_store_dwordx2 v[14:15], v[6:7], off nt
	v_cvt_pk_bf16_f32 v18, v2, v3
	v_cvt_pk_bf16_f32 v19, v4, v5
	ds_read_b128 v[2:5], v1 offset:9216
	ds_read_b128 v[6:9], v1 offset:25600
	global_store_dwordx2 v[16:17], v[18:19], off nt
	v_pk_mul_f32 v[78:79], v[78:79], v[96:97] op_sel_hi:[1,0]
	v_pk_mul_f32 v[80:81], v[80:81], v[96:97] op_sel_hi:[1,0]
	v_pk_mul_f32 v[82:83], v[82:83], v[96:97] op_sel_hi:[1,0]
	s_waitcnt lgkmcnt(0)
	v_pk_fma_f32 v[4:5], v[56:57], v[4:5], v[8:9]
	v_pk_fma_f32 v[2:3], v[54:55], v[2:3], v[6:7]
	v_cvt_pk_f16_f32 v7, v4, v5
	v_cvt_pk_f16_f32 v6, v2, v3
	global_store_dwordx2 v[14:15], v[6:7], off offset:512 nt
	v_cvt_pk_bf16_f32 v18, v2, v3
	v_cvt_pk_bf16_f32 v19, v4, v5
	ds_read_b128 v[2:5], v1 offset:10240
	ds_read_b128 v[6:9], v1 offset:26624
	global_store_dwordx2 v[16:17], v[18:19], off offset:512 nt
	v_pk_mul_f32 v[84:85], v[84:85], v[96:97] op_sel_hi:[1,0]
	s_waitcnt lgkmcnt(0)
	v_pk_fma_f32 v[4:5], v[62:63], v[4:5], v[8:9]
	v_pk_fma_f32 v[2:3], v[58:59], v[2:3], v[6:7]
	v_cvt_pk_f16_f32 v7, v4, v5
	v_cvt_pk_f16_f32 v6, v2, v3
	global_store_dwordx2 v[14:15], v[6:7], off offset:1024 nt
	v_cvt_pk_bf16_f32 v18, v2, v3
	v_cvt_pk_bf16_f32 v19, v4, v5
	ds_read_b128 v[2:5], v1 offset:11264
	ds_read_b128 v[6:9], v1 offset:27648
	global_store_dwordx2 v[16:17], v[18:19], off offset:1024 nt
	s_waitcnt lgkmcnt(0)
	v_pk_fma_f32 v[4:5], v[68:69], v[4:5], v[8:9]
	v_pk_fma_f32 v[2:3], v[66:67], v[2:3], v[6:7]
	v_cvt_pk_f16_f32 v7, v4, v5
	v_cvt_pk_f16_f32 v6, v2, v3
	global_store_dwordx2 v[14:15], v[6:7], off offset:1536 nt
	v_cvt_pk_bf16_f32 v2, v2, v3
	v_cvt_pk_bf16_f32 v3, v4, v5
	global_store_dwordx2 v[16:17], v[2:3], off offset:1536 nt
	ds_read_b128 v[2:5], v1 offset:12288
	ds_read_b128 v[6:9], v1 offset:28672
	s_waitcnt lgkmcnt(0)
	v_pk_fma_f32 v[4:5], v[72:73], v[4:5], v[8:9]
	v_pk_fma_f32 v[2:3], v[70:71], v[2:3], v[6:7]
	v_cvt_pk_f16_f32 v7, v4, v5
	v_cvt_pk_f16_f32 v6, v2, v3
	global_store_dwordx2 v[14:15], v[6:7], off offset:2048 nt
	v_cvt_pk_bf16_f32 v18, v2, v3
	v_cvt_pk_bf16_f32 v19, v4, v5
	ds_read_b128 v[2:5], v1 offset:13312
	ds_read_b128 v[6:9], v1 offset:29696
	global_store_dwordx2 v[16:17], v[18:19], off offset:2048 nt
	s_waitcnt lgkmcnt(0)
	v_pk_fma_f32 v[4:5], v[76:77], v[4:5], v[8:9]
	v_pk_fma_f32 v[2:3], v[74:75], v[2:3], v[6:7]
	v_cvt_pk_f16_f32 v7, v4, v5
	v_cvt_pk_f16_f32 v6, v2, v3
	global_store_dwordx2 v[14:15], v[6:7], off offset:2560 nt
	v_cvt_pk_bf16_f32 v18, v2, v3
	v_cvt_pk_bf16_f32 v19, v4, v5
	ds_read_b128 v[2:5], v1 offset:14336
	ds_read_b128 v[6:9], v1 offset:30720
	global_store_dwordx2 v[16:17], v[18:19], off offset:2560 nt
	s_waitcnt lgkmcnt(0)
	v_pk_fma_f32 v[4:5], v[80:81], v[4:5], v[8:9]
	v_pk_fma_f32 v[2:3], v[78:79], v[2:3], v[6:7]
	v_cvt_pk_f16_f32 v7, v4, v5
	v_cvt_pk_f16_f32 v6, v2, v3
	global_store_dwordx2 v[14:15], v[6:7], off offset:3072 nt
	v_cvt_pk_bf16_f32 v18, v2, v3
	v_cvt_pk_bf16_f32 v19, v4, v5
	ds_read_b128 v[2:5], v1 offset:15360
	ds_read_b128 v[6:9], v1 offset:31744
	global_store_dwordx2 v[16:17], v[18:19], off offset:3072 nt
	s_waitcnt lgkmcnt(0)
	v_pk_fma_f32 v[4:5], v[84:85], v[4:5], v[8:9]
	v_pk_fma_f32 v[2:3], v[82:83], v[2:3], v[6:7]
	v_cvt_pk_f16_f32 v7, v4, v5
	v_cvt_pk_f16_f32 v6, v2, v3
	global_store_dwordx2 v[14:15], v[6:7], off offset:3584 nt
	v_cvt_pk_bf16_f32 v2, v2, v3
	v_cvt_pk_bf16_f32 v3, v4, v5
	global_store_dwordx2 v[16:17], v[2:3], off offset:3584 nt
	s_cbranch_scc1 .LBB0_1101

.LBB0_1395:
	v_cmp_lt_i32_e32 vcc, v108, v107
	s_add_u32 s4, s6, s12
	s_addc_u32 s5, s7, s13
	v_cndmask_b32_e32 v4, v106, v108, vcc
	v_cmp_lt_i32_e32 vcc, v109, v107
	v_lshlrev_b32_e32 v133, 2, v4
	v_lshl_add_u64 v[2:3], v[36:37], 0, s[12:13]
	v_cndmask_b32_e32 v5, v106, v109, vcc
	v_cmp_lt_i32_e32 vcc, v110, v107
	v_lshlrev_b32_e32 v177, 2, v5
	v_lshl_add_u64 v[4:5], s[4:5], 0, v[34:35]
	v_cndmask_b32_e32 v6, v106, v110, vcc
	v_cmp_lt_i32_e32 vcc, v111, v107
	v_lshlrev_b32_e32 v180, 2, v6
	v_lshl_add_u64 v[40:41], v[4:5], 0, s[36:37]
	v_cndmask_b32_e32 v7, v106, v111, vcc
	v_cmp_lt_i32_e32 vcc, v112, v107
	v_lshlrev_b32_e32 v181, 2, v7
	v_lshl_add_u64 v[6:7], v[4:5], 0, s[34:35]
	v_cndmask_b32_e32 v8, v106, v112, vcc
	v_cmp_lt_i32_e32 vcc, v113, v107
	v_lshlrev_b32_e32 v182, 2, v8
	v_add_co_u32_e64 v38, s[4:5], s24, v4
	v_cndmask_b32_e32 v9, v106, v113, vcc
	v_add_co_u32_e32 v8, vcc, 0x2b200000, v4
	v_lshlrev_b32_e32 v183, 2, v9
	s_nop 0
	v_addc_co_u32_e32 v9, vcc, 0, v5, vcc
	global_load_dwordx2 v[42:43], v[6:7], off offset:512 nt
	global_load_dwordx2 v[44:45], v[6:7], off offset:1024 nt
	global_load_dwordx2 v[46:47], v[6:7], off offset:1536 nt
	global_load_dwordx2 v[48:49], v[6:7], off offset:2048 nt
	global_load_dwordx2 v[50:51], v[6:7], off offset:2560 nt
	global_load_dwordx2 v[52:53], v[6:7], off offset:3072 nt
	v_add_co_u32_e32 v4, vcc, s3, v4
	global_load_dwordx2 v[54:55], v[8:9], off nt
	global_load_dwordx2 v[56:57], v[6:7], off offset:3584 nt
	v_addc_co_u32_e64 v39, s[4:5], 0, v5, s[4:5]
	v_addc_co_u32_e32 v5, vcc, 0, v5, vcc
	global_load_dwordx2 v[58:59], v[4:5], off nt
	global_load_dwordx2 v[60:61], v[4:5], off offset:512 nt
	global_load_dwordx2 v[62:63], v[4:5], off offset:1024 nt
	global_load_dwordx2 v[64:65], v[4:5], off offset:1536 nt
	global_load_dwordx2 v[66:67], v[4:5], off offset:2048 nt
	global_load_dwordx2 v[68:69], v[4:5], off offset:2560 nt
	global_load_dwordx2 v[70:71], v[4:5], off offset:3072 nt
	global_load_dwordx2 v[72:73], v[4:5], off offset:3584 nt
	v_add_co_u32_e32 v6, vcc, s9, v2
	v_mov_b32_e32 v117, 0
	s_nop 0
	v_addc_co_u32_e32 v7, vcc, 0, v3, vcc
	v_add_co_u32_e32 v2, vcc, s11, v2
	v_mov_b32_e32 v118, 0
	s_nop 0
	v_addc_co_u32_e32 v3, vcc, 0, v3, vcc
	global_load_dwordx2 v[74:75], v[6:7], off offset:512 nt
	global_load_dwordx2 v[76:77], v[6:7], off offset:1024 nt
	global_load_dwordx2 v[78:79], v[6:7], off offset:1536 nt
	global_load_dwordx2 v[80:81], v[6:7], off offset:2048 nt
	global_load_dwordx2 v[82:83], v[6:7], off offset:2560 nt
	global_load_dwordx2 v[84:85], v[6:7], off offset:3072 nt
	global_load_dwordx2 v[86:87], v[2:3], off offset:-4096 nt
	global_load_dwordx2 v[88:89], v[6:7], off offset:3584 nt
	global_load_dwordx2 v[90:91], v[2:3], off nt
	global_load_dwordx2 v[92:93], v[2:3], off offset:512 nt
	global_load_dwordx2 v[94:95], v[2:3], off offset:1024 nt
	global_load_dwordx2 v[96:97], v[2:3], off offset:1536 nt
	global_load_dwordx2 v[98:99], v[2:3], off offset:2048 nt
	global_load_dwordx2 v[100:101], v[2:3], off offset:2560 nt
	global_load_dwordx2 v[102:103], v[2:3], off offset:3072 nt
	global_load_dwordx2 v[104:105], v[2:3], off offset:3584 nt
	ds_read_b128 v[10:13], v1
	ds_read_b128 v[2:5], v1 offset:1024
	ds_read_b128 v[26:29], v1 offset:16384
	ds_read_b128 v[18:21], v1 offset:17408
	ds_read_b128 v[14:17], v1 offset:2048
	ds_read_b128 v[6:9], v1 offset:3072
	ds_read_b128 v[30:33], v1 offset:18432
	ds_read_b128 v[22:25], v1 offset:19456
	v_mov_b32_e32 v119, 0
	v_mov_b32_e32 v121, 0
	v_mov_b32_e32 v120, 0
	v_mov_b32_e32 v122, 0
	v_mov_b32_e32 v123, 0
	v_mov_b32_e32 v125, 0
	v_mov_b32_e32 v124, 0
	v_mov_b32_e32 v126, 0
	v_mov_b32_e32 v127, 0
	v_mov_b32_e32 v129, 0
	v_mov_b32_e32 v128, 0
	v_mov_b32_e32 v130, 0
	v_mov_b32_e32 v131, 0
	v_mov_b32_e32 v132, 0
	s_add_i32 s8, s8, s10
	v_lshl_add_u64 v[36:37], v[36:37], 0, s[14:15]
	s_waitcnt vmcnt(31)
	v_lshlrev_b32_e32 v134, 16, v42
	v_and_b32_e32 v135, 0xffff0000, v42
	v_lshlrev_b32_e32 v136, 16, v43
	v_and_b32_e32 v137, 0xffff0000, v43
	s_waitcnt vmcnt(28)
	v_lshlrev_b32_e32 v146, 16, v48
	v_and_b32_e32 v147, 0xffff0000, v48
	v_lshlrev_b32_e32 v138, 16, v44
	s_waitcnt vmcnt(25)
	v_lshlrev_b32_e32 v158, 16, v54
	v_and_b32_e32 v159, 0xffff0000, v54
	v_lshlrev_b32_e32 v160, 16, v55
	v_and_b32_e32 v161, 0xffff0000, v55
	s_waitcnt vmcnt(19)
	v_lshlrev_b32_e32 v187, 16, v66
	v_and_b32_e32 v188, 0xffff0000, v66
	v_lshlrev_b32_e32 v189, 16, v67
	v_and_b32_e32 v190, 0xffff0000, v67
	s_waitcnt vmcnt(18)
	v_lshlrev_b32_e32 v191, 16, v68
	v_and_b32_e32 v192, 0xffff0000, v68
	v_lshlrev_b32_e32 v193, 16, v69
	v_and_b32_e32 v194, 0xffff0000, v69
	s_waitcnt vmcnt(9)
	v_fma_mix_f32 v66, v86, s18, v158 op_sel_hi:[1,0,0]
	v_fma_mix_f32 v67, v86, s18, v159 op_sel:[1,0,0] op_sel_hi:[1,0,0]
	v_fma_mix_f32 v68, v87, s18, v160 op_sel_hi:[1,0,0]
	v_fma_mix_f32 v69, v87, s18, v161 op_sel:[1,0,0] op_sel_hi:[1,0,0]
	v_and_b32_e32 v139, 0xffff0000, v44
	v_lshlrev_b32_e32 v140, 16, v45
	v_and_b32_e32 v141, 0xffff0000, v45
	v_fma_mix_f32 v42, v74, s18, v134 op_sel_hi:[1,0,0]
	v_fma_mix_f32 v43, v74, s18, v135 op_sel:[1,0,0] op_sel_hi:[1,0,0]
	v_fma_mix_f32 v44, v75, s18, v136 op_sel_hi:[1,0,0]
	v_fma_mix_f32 v45, v75, s18, v137 op_sel:[1,0,0] op_sel_hi:[1,0,0]
	v_fma_mix_f32 v54, v80, s18, v146 op_sel_hi:[1,0,0]
	v_fma_mix_f32 v55, v80, s18, v147 op_sel:[1,0,0] op_sel_hi:[1,0,0]
	v_add_f32_e32 v146, v66, v67
	v_add_f32_e32 v147, v68, v69
	v_lshlrev_b32_e32 v142, 16, v46
	v_and_b32_e32 v143, 0xffff0000, v46
	v_lshlrev_b32_e32 v144, 16, v47
	v_and_b32_e32 v145, 0xffff0000, v47
	v_lshlrev_b32_e32 v148, 16, v49
	v_and_b32_e32 v149, 0xffff0000, v49
	v_fma_mix_f32 v46, v76, s18, v138 op_sel_hi:[1,0,0]
	v_fma_mix_f32 v47, v76, s18, v139 op_sel:[1,0,0] op_sel_hi:[1,0,0]
	v_fma_mix_f32 v48, v77, s18, v140 op_sel_hi:[1,0,0]
	v_fma_mix_f32 v49, v77, s18, v141 op_sel:[1,0,0] op_sel_hi:[1,0,0]
	v_add_f32_e32 v134, v42, v43
	v_add_f32_e32 v135, v44, v45
	v_add_f32_e32 v146, v146, v147
	v_lshlrev_b32_e32 v150, 16, v50
	v_and_b32_e32 v151, 0xffff0000, v50
	v_lshlrev_b32_e32 v152, 16, v51
	v_and_b32_e32 v153, 0xffff0000, v51
	v_lshlrev_b32_e32 v154, 16, v52
	v_and_b32_e32 v155, 0xffff0000, v52
	v_lshlrev_b32_e32 v156, 16, v53
	v_and_b32_e32 v157, 0xffff0000, v53
	v_fma_mix_f32 v50, v78, s18, v142 op_sel_hi:[1,0,0]
	v_fma_mix_f32 v51, v78, s18, v143 op_sel:[1,0,0] op_sel_hi:[1,0,0]
	v_fma_mix_f32 v52, v79, s18, v144 op_sel_hi:[1,0,0]
	v_fma_mix_f32 v53, v79, s18, v145 op_sel:[1,0,0] op_sel_hi:[1,0,0]
	v_add_f32_e32 v136, v46, v47
	v_add_f32_e32 v137, v48, v49
	v_add_f32_e32 v134, v134, v135
	v_add_f32_e32 v146, 0, v146
	v_lshlrev_b32_e32 v162, 16, v56
	v_and_b32_e32 v163, 0xffff0000, v56
	v_lshlrev_b32_e32 v164, 16, v57
	v_and_b32_e32 v165, 0xffff0000, v57
	v_fma_mix_f32 v56, v81, s18, v148 op_sel_hi:[1,0,0]
	v_fma_mix_f32 v57, v81, s18, v149 op_sel:[1,0,0] op_sel_hi:[1,0,0]
	v_add_f32_e32 v138, v50, v51
	v_add_f32_e32 v139, v52, v53
	v_add_f32_e32 v135, v136, v137
	v_add_f32_e32 v134, v146, v134
	v_lshlrev_b32_e32 v166, 16, v58
	v_and_b32_e32 v167, 0xffff0000, v58
	v_lshlrev_b32_e32 v168, 16, v59
	v_and_b32_e32 v169, 0xffff0000, v59
	v_lshlrev_b32_e32 v170, 16, v60
	v_and_b32_e32 v171, 0xffff0000, v60
	v_lshlrev_b32_e32 v172, 16, v61
	v_and_b32_e32 v173, 0xffff0000, v61
	v_fma_mix_f32 v58, v82, s18, v150 op_sel_hi:[1,0,0]
	v_fma_mix_f32 v59, v82, s18, v151 op_sel:[1,0,0] op_sel_hi:[1,0,0]
	v_fma_mix_f32 v60, v83, s18, v152 op_sel_hi:[1,0,0]
	v_fma_mix_f32 v61, v83, s18, v153 op_sel:[1,0,0] op_sel_hi:[1,0,0]
	v_add_f32_e32 v140, v54, v55
	v_add_f32_e32 v141, v56, v57
	v_add_f32_e32 v136, v138, v139
	v_add_f32_e32 v134, v134, v135
	v_lshlrev_b32_e32 v174, 16, v62
	v_and_b32_e32 v175, 0xffff0000, v62
	v_lshlrev_b32_e32 v176, 16, v63
	v_and_b32_e32 v178, 0xffff0000, v63
	v_lshlrev_b32_e32 v179, 16, v64
	v_and_b32_e32 v184, 0xffff0000, v64
	v_lshlrev_b32_e32 v185, 16, v65
	v_and_b32_e32 v186, 0xffff0000, v65
	v_fma_mix_f32 v62, v84, s18, v154 op_sel_hi:[1,0,0]
	v_fma_mix_f32 v63, v84, s18, v155 op_sel:[1,0,0] op_sel_hi:[1,0,0]
	v_fma_mix_f32 v64, v85, s18, v156 op_sel_hi:[1,0,0]
	v_fma_mix_f32 v65, v85, s18, v157 op_sel:[1,0,0] op_sel_hi:[1,0,0]
	v_add_f32_e32 v142, v58, v59
	v_add_f32_e32 v143, v60, v61
	v_add_f32_e32 v137, v140, v141
	v_add_f32_e32 v134, v134, v136
	v_lshlrev_b32_e32 v195, 16, v70
	v_and_b32_e32 v196, 0xffff0000, v70
	v_lshlrev_b32_e32 v197, 16, v71
	v_and_b32_e32 v198, 0xffff0000, v71
	v_lshlrev_b32_e32 v199, 16, v72
	v_and_b32_e32 v200, 0xffff0000, v72
	v_lshlrev_b32_e32 v201, 16, v73
	v_and_b32_e32 v202, 0xffff0000, v73
	v_add_f32_e32 v144, v62, v63
	v_add_f32_e32 v145, v64, v65
	s_waitcnt vmcnt(8)
	v_fma_mix_f32 v70, v88, s18, v162 op_sel_hi:[1,0,0]
	v_fma_mix_f32 v71, v88, s18, v163 op_sel:[1,0,0] op_sel_hi:[1,0,0]
	v_fma_mix_f32 v72, v89, s18, v164 op_sel_hi:[1,0,0]
	v_fma_mix_f32 v73, v89, s18, v165 op_sel:[1,0,0] op_sel_hi:[1,0,0]
	v_add_f32_e32 v138, v142, v143
	v_add_f32_e32 v134, v134, v137
	s_waitcnt vmcnt(7)
	v_fma_mix_f32 v74, v90, s18, v166 op_sel_hi:[1,0,0]
	v_fma_mix_f32 v75, v90, s18, v167 op_sel:[1,0,0] op_sel_hi:[1,0,0]
	v_fma_mix_f32 v76, v91, s18, v168 op_sel_hi:[1,0,0]
	v_fma_mix_f32 v77, v91, s18, v169 op_sel:[1,0,0] op_sel_hi:[1,0,0]
	v_add_f32_e32 v139, v144, v145
	v_add_f32_e32 v140, v70, v71
	v_add_f32_e32 v141, v72, v73
	v_add_f32_e32 v134, v134, v138
	s_waitcnt vmcnt(6)
	v_fma_mix_f32 v78, v92, s18, v170 op_sel_hi:[1,0,0]
	v_fma_mix_f32 v79, v92, s18, v171 op_sel:[1,0,0] op_sel_hi:[1,0,0]
	v_fma_mix_f32 v80, v93, s18, v172 op_sel_hi:[1,0,0]
	v_fma_mix_f32 v81, v93, s18, v173 op_sel:[1,0,0] op_sel_hi:[1,0,0]
	v_add_f32_e32 v142, v74, v75
	v_add_f32_e32 v143, v76, v77
	v_add_f32_e32 v140, v140, v141
	v_add_f32_e32 v134, v134, v139
	s_waitcnt vmcnt(5)
	v_fma_mix_f32 v82, v94, s18, v174 op_sel_hi:[1,0,0]
	v_fma_mix_f32 v83, v94, s18, v175 op_sel:[1,0,0] op_sel_hi:[1,0,0]
	v_fma_mix_f32 v84, v95, s18, v176 op_sel_hi:[1,0,0]
	v_fma_mix_f32 v85, v95, s18, v178 op_sel:[1,0,0] op_sel_hi:[1,0,0]
	v_add_f32_e32 v144, v78, v79
	v_add_f32_e32 v145, v80, v81
	v_add_f32_e32 v141, v142, v143
	v_add_f32_e32 v134, v134, v140
	s_waitcnt vmcnt(4)
	v_fma_mix_f32 v86, v96, s18, v179 op_sel_hi:[1,0,0]
	v_fma_mix_f32 v87, v96, s18, v184 op_sel:[1,0,0] op_sel_hi:[1,0,0]
	v_fma_mix_f32 v88, v97, s18, v185 op_sel_hi:[1,0,0]
	v_fma_mix_f32 v89, v97, s18, v186 op_sel:[1,0,0] op_sel_hi:[1,0,0]
	v_add_f32_e32 v148, v82, v83
	v_add_f32_e32 v149, v84, v85
	v_add_f32_e32 v142, v144, v145
	v_add_f32_e32 v134, v134, v141
	s_waitcnt vmcnt(3)
	v_fma_mix_f32 v90, v98, s18, v187 op_sel_hi:[1,0,0]
	v_fma_mix_f32 v91, v98, s18, v188 op_sel:[1,0,0] op_sel_hi:[1,0,0]
	v_fma_mix_f32 v92, v99, s18, v189 op_sel_hi:[1,0,0]
	v_fma_mix_f32 v93, v99, s18, v190 op_sel:[1,0,0] op_sel_hi:[1,0,0]
	v_add_f32_e32 v150, v86, v87
	v_add_f32_e32 v151, v88, v89
	v_add_f32_e32 v143, v148, v149
	v_add_f32_e32 v134, v134, v142
	s_waitcnt vmcnt(2)
	v_fma_mix_f32 v94, v100, s18, v191 op_sel_hi:[1,0,0]
	v_fma_mix_f32 v95, v100, s18, v192 op_sel:[1,0,0] op_sel_hi:[1,0,0]
	v_fma_mix_f32 v96, v101, s18, v193 op_sel_hi:[1,0,0]
	v_fma_mix_f32 v97, v101, s18, v194 op_sel:[1,0,0] op_sel_hi:[1,0,0]
	v_add_f32_e32 v152, v90, v91
	v_add_f32_e32 v153, v92, v93
	v_add_f32_e32 v144, v150, v151
	v_add_f32_e32 v134, v134, v143
	s_waitcnt vmcnt(1)
	v_fma_mix_f32 v98, v102, s18, v195 op_sel_hi:[1,0,0]
	v_fma_mix_f32 v99, v102, s18, v196 op_sel:[1,0,0] op_sel_hi:[1,0,0]
	v_fma_mix_f32 v100, v103, s18, v197 op_sel_hi:[1,0,0]
	v_fma_mix_f32 v101, v103, s18, v198 op_sel:[1,0,0] op_sel_hi:[1,0,0]
	v_add_f32_e32 v154, v94, v95
	v_add_f32_e32 v155, v96, v97
	v_add_f32_e32 v145, v152, v153
	v_add_f32_e32 v134, v134, v144
	s_waitcnt vmcnt(0)
	v_fma_mix_f32 v102, v104, s18, v199 op_sel_hi:[1,0,0]
	v_fma_mix_f32 v103, v104, s18, v200 op_sel:[1,0,0] op_sel_hi:[1,0,0]
	v_fma_mix_f32 v104, v105, s18, v201 op_sel_hi:[1,0,0]
	v_fma_mix_f32 v105, v105, s18, v202 op_sel:[1,0,0] op_sel_hi:[1,0,0]
	v_add_f32_e32 v156, v98, v99
	v_add_f32_e32 v157, v100, v101
	v_add_f32_e32 v147, v154, v155
	v_add_f32_e32 v134, v134, v145
	v_add_f32_e32 v158, v102, v103
	v_add_f32_e32 v159, v104, v105
	v_add_f32_e32 v148, v156, v157
	v_add_f32_e32 v134, v134, v147
	v_add_f32_e32 v149, v158, v159
	v_add_f32_e32 v134, v134, v148
	v_add_f32_e32 v134, v134, v149
	ds_bpermute_b32 v135, v133, v134
	s_waitcnt lgkmcnt(0)
	v_add_f32_e32 v134, v134, v135
	ds_bpermute_b32 v135, v177, v134
	s_waitcnt lgkmcnt(0)
	v_add_f32_e32 v134, v134, v135
	ds_bpermute_b32 v135, v180, v134
	s_waitcnt lgkmcnt(0)
	v_add_f32_e32 v134, v134, v135
	ds_bpermute_b32 v135, v181, v134
	s_waitcnt lgkmcnt(0)
	v_add_f32_e32 v134, v134, v135
	ds_bpermute_b32 v135, v182, v134
	s_waitcnt lgkmcnt(0)
	v_add_f32_e32 v134, v134, v135
	ds_bpermute_b32 v135, v183, v134
	s_waitcnt lgkmcnt(0)
	v_add_f32_e32 v134, v134, v135
	v_fmac_f32_e32 v67, 0xb9800000, v134
	v_fmac_f32_e32 v66, 0xb9800000, v134
	v_fmac_f32_e32 v69, 0xb9800000, v134
	v_fmac_f32_e32 v68, 0xb9800000, v134
	v_fmac_f32_e32 v43, 0xb9800000, v134
	v_fmac_f32_e32 v42, 0xb9800000, v134
	v_fmac_f32_e32 v45, 0xb9800000, v134
	v_fmac_f32_e32 v44, 0xb9800000, v134
	v_fmac_f32_e32 v47, 0xb9800000, v134
	v_fmac_f32_e32 v46, 0xb9800000, v134
	v_fmac_f32_e32 v49, 0xb9800000, v134
	v_fmac_f32_e32 v48, 0xb9800000, v134
	v_fmac_f32_e32 v53, 0xb9800000, v134
	v_fmac_f32_e32 v52, 0xb9800000, v134
	v_fmac_f32_e32 v51, 0xb9800000, v134
	v_fmac_f32_e32 v50, 0xb9800000, v134
	v_fmac_f32_e32 v55, 0xb9800000, v134
	v_fmac_f32_e32 v54, 0xb9800000, v134
	v_fmac_f32_e32 v57, 0xb9800000, v134
	v_fmac_f32_e32 v56, 0xb9800000, v134
	v_fmac_f32_e32 v59, 0xb9800000, v134
	v_fmac_f32_e32 v58, 0xb9800000, v134
	v_fmac_f32_e32 v61, 0xb9800000, v134
	v_fmac_f32_e32 v60, 0xb9800000, v134
	v_fmac_f32_e32 v65, 0xb9800000, v134
	v_fmac_f32_e32 v64, 0xb9800000, v134
	v_fmac_f32_e32 v63, 0xb9800000, v134
	v_fmac_f32_e32 v62, 0xb9800000, v134
	v_fmac_f32_e32 v71, 0xb9800000, v134
	v_fmac_f32_e32 v70, 0xb9800000, v134
	v_fmac_f32_e32 v73, 0xb9800000, v134
	v_fmac_f32_e32 v72, 0xb9800000, v134
	v_fmac_f32_e32 v75, 0xb9800000, v134
	v_fmac_f32_e32 v74, 0xb9800000, v134
	v_fmac_f32_e32 v77, 0xb9800000, v134
	v_fmac_f32_e32 v76, 0xb9800000, v134
	v_fmac_f32_e32 v81, 0xb9800000, v134
	v_fmac_f32_e32 v80, 0xb9800000, v134
	v_fmac_f32_e32 v79, 0xb9800000, v134
	v_fmac_f32_e32 v78, 0xb9800000, v134
	v_fmac_f32_e32 v83, 0xb9800000, v134
	v_fmac_f32_e32 v82, 0xb9800000, v134
	v_fmac_f32_e32 v85, 0xb9800000, v134
	v_fmac_f32_e32 v84, 0xb9800000, v134
	v_fmac_f32_e32 v87, 0xb9800000, v134
	v_fmac_f32_e32 v86, 0xb9800000, v134
	v_fmac_f32_e32 v89, 0xb9800000, v134
	v_fmac_f32_e32 v88, 0xb9800000, v134
	v_fmac_f32_e32 v93, 0xb9800000, v134
	v_fmac_f32_e32 v92, 0xb9800000, v134
	v_fmac_f32_e32 v91, 0xb9800000, v134
	v_fmac_f32_e32 v90, 0xb9800000, v134
	v_fmac_f32_e32 v95, 0xb9800000, v134
	v_fmac_f32_e32 v94, 0xb9800000, v134
	v_fmac_f32_e32 v97, 0xb9800000, v134
	v_fmac_f32_e32 v96, 0xb9800000, v134
	v_fmac_f32_e32 v99, 0xb9800000, v134
	v_fmac_f32_e32 v98, 0xb9800000, v134
	v_fmac_f32_e32 v101, 0xb9800000, v134
	v_fmac_f32_e32 v100, 0xb9800000, v134
	v_fmac_f32_e32 v105, 0xb9800000, v134
	v_fmac_f32_e32 v104, 0xb9800000, v134
	v_fmac_f32_e32 v103, 0xb9800000, v134
	v_fmac_f32_e32 v102, 0xb9800000, v134
	v_pk_mul_f32 v[134:135], v[68:69], v[68:69]
	v_pk_mul_f32 v[136:137], v[66:67], v[66:67]
	v_pk_mul_f32 v[138:139], v[44:45], v[44:45]
	v_pk_mul_f32 v[140:141], v[42:43], v[42:43]
	v_pk_mov_b32 v[178:179], v[136:137], v[134:135] op_sel:[1,0]
	v_mov_b32_e32 v137, v135
	v_pk_mov_b32 v[134:135], v[140:141], v[138:139] op_sel:[1,0]
	v_mov_b32_e32 v141, v139
	v_mul_f32_e32 v142, v46, v46
	v_mul_f32_e32 v144, v48, v48
	v_pk_add_f32 v[136:137], v[178:179], v[136:137]
	v_pk_add_f32 v[134:135], v[134:135], v[140:141]
	v_pk_fma_f32 v[138:139], v[46:47], v[46:47], v[142:143] op_sel_hi:[1,1,0]
	v_pk_fma_f32 v[142:143], v[48:49], v[48:49], v[144:145] op_sel_hi:[1,1,0]
	v_pk_add_f32 v[136:137], v[136:137], v[136:137] op_sel_hi:[0,1]
	v_pk_add_f32 v[134:135], v[134:135], v[134:135] op_sel_hi:[0,1]
	v_pk_mul_f32 v[146:147], v[56:57], v[56:57]
	v_pk_mul_f32 v[148:149], v[54:55], v[54:55]
	v_mul_f32_e32 v138, v50, v50
	v_mul_f32_e32 v142, v51, v51
	v_mul_f32_e32 v136, v52, v52
	v_mul_f32_e32 v134, v53, v53
	v_pk_mov_b32 v[144:145], v[148:149], v[146:147] op_sel:[1,0]
	v_mov_b32_e32 v149, v147
	v_pk_add_f32 v[138:139], v[138:139], v[142:143]
	v_pk_add_f32 v[134:135], v[136:137], v[134:135]
	v_mul_f32_e32 v150, v58, v58
	v_mul_f32_e32 v152, v60, v60
	v_pk_add_f32 v[140:141], v[144:145], v[148:149]
	v_pk_add_f32 v[134:135], v[138:139], v[134:135]
	v_pk_fma_f32 v[146:147], v[58:59], v[58:59], v[150:151] op_sel_hi:[1,1,0]
	v_pk_fma_f32 v[150:151], v[60:61], v[60:61], v[152:153] op_sel_hi:[1,1,0]
	v_pk_add_f32 v[140:141], v[140:141], v[140:141] op_sel_hi:[0,1]
	v_pk_add_f32 v[134:135], v[134:135], v[134:135] op_sel_hi:[0,1]
	v_pk_mul_f32 v[154:155], v[72:73], v[72:73]
	v_pk_mul_f32 v[156:157], v[70:71], v[70:71]
	v_mul_f32_e32 v146, v62, v62
	v_mul_f32_e32 v150, v63, v63
	v_mul_f32_e32 v140, v64, v64
	v_mul_f32_e32 v134, v65, v65
	v_pk_mov_b32 v[152:153], v[156:157], v[154:155] op_sel:[1,0]
	v_mov_b32_e32 v157, v155
	v_pk_add_f32 v[142:143], v[146:147], v[150:151]
	v_pk_add_f32 v[134:135], v[140:141], v[134:135]
	v_mul_f32_e32 v158, v74, v74
	v_mul_f32_e32 v160, v76, v76
	v_pk_add_f32 v[144:145], v[152:153], v[156:157]
	v_pk_add_f32 v[134:135], v[142:143], v[134:135]
	v_pk_fma_f32 v[154:155], v[74:75], v[74:75], v[158:159] op_sel_hi:[1,1,0]
	v_pk_fma_f32 v[158:159], v[76:77], v[76:77], v[160:161] op_sel_hi:[1,1,0]
	v_pk_add_f32 v[144:145], v[144:145], v[144:145] op_sel_hi:[0,1]
	v_pk_add_f32 v[134:135], v[134:135], v[134:135] op_sel_hi:[0,1]
	v_pk_mul_f32 v[162:163], v[84:85], v[84:85]
	v_pk_mul_f32 v[164:165], v[82:83], v[82:83]
	v_mul_f32_e32 v154, v78, v78
	v_mul_f32_e32 v158, v79, v79
	v_mul_f32_e32 v144, v80, v80
	v_mul_f32_e32 v134, v81, v81
	v_pk_mov_b32 v[160:161], v[164:165], v[162:163] op_sel:[1,0]
	v_mov_b32_e32 v165, v163
	v_pk_add_f32 v[146:147], v[154:155], v[158:159]
	v_pk_add_f32 v[134:135], v[144:145], v[134:135]
	v_mul_f32_e32 v166, v86, v86
	v_mul_f32_e32 v168, v88, v88
	v_pk_add_f32 v[148:149], v[160:161], v[164:165]
	v_pk_add_f32 v[134:135], v[146:147], v[134:135]
	v_pk_fma_f32 v[162:163], v[86:87], v[86:87], v[166:167] op_sel_hi:[1,1,0]
	v_pk_fma_f32 v[166:167], v[88:89], v[88:89], v[168:169] op_sel_hi:[1,1,0]
	v_pk_add_f32 v[148:149], v[148:149], v[148:149] op_sel_hi:[0,1]
	v_pk_add_f32 v[134:135], v[134:135], v[134:135] op_sel_hi:[0,1]
	v_pk_mul_f32 v[170:171], v[96:97], v[96:97]
	v_pk_mul_f32 v[172:173], v[94:95], v[94:95]
	v_mul_f32_e32 v162, v90, v90
	v_mul_f32_e32 v166, v91, v91
	v_mul_f32_e32 v148, v92, v92
	v_mul_f32_e32 v134, v93, v93
	v_pk_mov_b32 v[168:169], v[172:173], v[170:171] op_sel:[1,0]
	v_mov_b32_e32 v173, v171
	v_pk_add_f32 v[150:151], v[162:163], v[166:167]
	v_pk_add_f32 v[134:135], v[148:149], v[134:135]
	v_mul_f32_e32 v174, v98, v98
	v_mul_f32_e32 v176, v100, v100
	v_pk_add_f32 v[152:153], v[168:169], v[172:173]
	v_pk_add_f32 v[134:135], v[150:151], v[134:135]
	v_pk_fma_f32 v[170:171], v[98:99], v[98:99], v[174:175] op_sel_hi:[1,1,0]
	v_pk_fma_f32 v[174:175], v[100:101], v[100:101], v[176:177] op_sel_hi:[1,1,0]
	v_pk_add_f32 v[152:153], v[152:153], v[152:153] op_sel_hi:[0,1]
	v_pk_add_f32 v[134:135], v[134:135], v[134:135] op_sel_hi:[0,1]
	v_mul_f32_e32 v170, v102, v102
	v_mul_f32_e32 v174, v103, v103
	v_mul_f32_e32 v152, v104, v104
	v_mul_f32_e32 v134, v105, v105
	v_pk_add_f32 v[154:155], v[170:171], v[174:175]
	v_pk_add_f32 v[134:135], v[152:153], v[134:135]
	s_nop 0
	v_pk_add_f32 v[134:135], v[154:155], v[134:135]
	s_nop 0
	v_add_f32_e32 v134, v134, v135
	ds_bpermute_b32 v133, v133, v134
	s_waitcnt lgkmcnt(0)
	v_add_f32_e32 v133, v134, v133
	ds_bpermute_b32 v134, v177, v133
	s_waitcnt lgkmcnt(0)
	v_add_f32_e32 v133, v133, v134
	ds_bpermute_b32 v134, v180, v133
	s_waitcnt lgkmcnt(0)
	v_add_f32_e32 v133, v133, v134
	ds_bpermute_b32 v134, v181, v133
	s_waitcnt lgkmcnt(0)
	v_add_f32_e32 v133, v133, v134
	ds_bpermute_b32 v134, v182, v133
	s_waitcnt lgkmcnt(0)
	v_add_f32_e32 v133, v133, v134
	ds_bpermute_b32 v134, v183, v133
	s_waitcnt lgkmcnt(0)
	v_add_f32_e32 v133, v133, v134
	v_fmamk_f32 v133, v133, 0x39800000, v114
	v_mul_f32_e32 v134, 0x4f800000, v133
	v_cmp_gt_f32_e32 vcc, s19, v133
	s_nop 1
	v_cndmask_b32_e32 v133, v133, v134, vcc
	v_sqrt_f32_e32 v134, v133
	s_nop 0
	v_add_u32_e32 v135, -1, v134
	v_add_u32_e32 v136, 1, v134
	v_fma_f32 v137, -v135, v134, v133
	v_fma_f32 v138, -v136, v134, v133
	v_cmp_ge_f32_e64 s[4:5], 0, v137
	s_nop 1
	v_cndmask_b32_e64 v134, v134, v135, s[4:5]
	v_cmp_lt_f32_e64 s[4:5], 0, v138
	s_nop 1
	v_cndmask_b32_e64 v134, v134, v136, s[4:5]
	v_mul_f32_e32 v135, 0x37800000, v134
	v_cndmask_b32_e32 v134, v134, v135, vcc
	v_cmp_class_f32_e32 vcc, v133, v115
	s_nop 1
	v_cndmask_b32_e32 v133, v134, v133, vcc
	v_div_scale_f32 v134, s[4:5], v133, v133, 1.0
	v_rcp_f32_e32 v136, v134
	v_div_scale_f32 v135, vcc, 1.0, v133, 1.0
	v_fma_f32 v137, -v134, v136, 1.0
	v_fmac_f32_e32 v136, v137, v136
	v_mul_f32_e32 v137, v135, v136
	v_fma_f32 v138, -v134, v137, v135
	v_fmac_f32_e32 v137, v138, v136
	v_fma_f32 v134, -v134, v137, v135
	v_div_fmas_f32 v134, v134, v136, v137
	v_div_fixup_f32 v134, v134, v133, 1.0
	v_pk_mul_f32 v[66:67], v[66:67], v[134:135] op_sel_hi:[1,0]
	v_pk_mul_f32 v[42:43], v[42:43], v[134:135] op_sel_hi:[1,0]
	v_pk_fma_f32 v[10:11], v[10:11], v[66:67], v[26:27]
	v_pk_fma_f32 v[2:3], v[2:3], v[42:43], v[18:19]
	v_cvt_pk_fp8_f32 v117, v10, v11
	v_pk_mul_f32 v[68:69], v[68:69], v[134:135] op_sel_hi:[1,0]
	v_pk_mul_f32 v[46:47], v[46:47], v[134:135] op_sel_hi:[1,0]
	v_pk_mul_f32 v[50:51], v[50:51], v[134:135] op_sel_hi:[1,0]
	v_cvt_pk_fp8_f32 v118, v2, v3
	v_pk_fma_f32 v[12:13], v[12:13], v[68:69], v[28:29]
	v_pk_fma_f32 v[14:15], v[14:15], v[46:47], v[30:31]
	v_pk_fma_f32 v[6:7], v[6:7], v[50:51], v[22:23]
	v_pk_mul_f32 v[44:45], v[44:45], v[134:135] op_sel_hi:[1,0]
	v_cvt_pk_fp8_f32 v119, v14, v15
	v_cvt_pk_fp8_f32 v121, v6, v7
	v_cvt_pk_fp8_f32 v117, v12, v13 op_sel:[0,0,1]
	v_pk_fma_f32 v[4:5], v[4:5], v[44:45], v[20:21]
	v_pk_mul_f32 v[48:49], v[48:49], v[134:135] op_sel_hi:[1,0]
	v_pk_mul_f32 v[52:53], v[52:53], v[134:135] op_sel_hi:[1,0]
	v_cvt_pk_fp8_f32 v118, v4, v5 op_sel:[0,0,1]
	v_pk_fma_f32 v[16:17], v[16:17], v[48:49], v[32:33]
	v_pk_fma_f32 v[8:9], v[8:9], v[52:53], v[24:25]
	v_cvt_pk_f16_f32 v19, v12, v13
	v_cvt_pk_f16_f32 v18, v10, v11
	v_cvt_pk_f16_f32 v11, v4, v5
	v_cvt_pk_f16_f32 v10, v2, v3
	v_cvt_pk_f16_f32 v3, v16, v17
	v_cvt_pk_f16_f32 v2, v14, v15
	v_cvt_pk_f16_f32 v15, v8, v9
	v_cvt_pk_f16_f32 v14, v6, v7
	global_store_dwordx2 v[38:39], v[18:19], off offset:-4096 nt
	v_cvt_pk_fp8_f32 v119, v16, v17 op_sel:[0,0,1]
	v_cvt_pk_fp8_f32 v121, v8, v9 op_sel:[0,0,1]
	global_store_dword v116, v117, s[16:17] nt
	global_store_dwordx2 v[40:41], v[10:11], off offset:512 nt
	global_store_dword v116, v118, s[16:17] offset:256 nt
	global_store_dwordx2 v[40:41], v[2:3], off offset:1024 nt
	global_store_dword v116, v119, s[16:17] offset:512 nt
	global_store_dwordx2 v[40:41], v[14:15], off offset:1536 nt
	global_store_dword v116, v121, s[16:17] offset:768 nt
	v_pk_mul_f32 v[54:55], v[54:55], v[134:135] op_sel_hi:[1,0]
	ds_read_b128 v[2:5], v1 offset:4096
	ds_read_b128 v[6:9], v1 offset:5120
	ds_read_b128 v[10:13], v1 offset:20480
	ds_read_b128 v[14:17], v1 offset:21504
	ds_read_b128 v[18:21], v1 offset:6144
	ds_read_b128 v[22:25], v1 offset:7168
	ds_read_b128 v[26:29], v1 offset:22528
	ds_read_b128 v[30:33], v1 offset:23552
	s_waitcnt lgkmcnt(5)
	v_pk_fma_f32 v[2:3], v[2:3], v[54:55], v[10:11]
	v_pk_mul_f32 v[58:59], v[58:59], v[134:135] op_sel_hi:[1,0]
	v_cvt_pk_fp8_f32 v120, v2, v3
	s_waitcnt lgkmcnt(4)
	v_pk_fma_f32 v[6:7], v[6:7], v[58:59], v[14:15]
	v_pk_mul_f32 v[56:57], v[56:57], v[134:135] op_sel_hi:[1,0]
	v_pk_mul_f32 v[60:61], v[60:61], v[134:135] op_sel_hi:[1,0]
	v_pk_mul_f32 v[62:63], v[62:63], v[134:135] op_sel_hi:[1,0]
	v_pk_mul_f32 v[70:71], v[70:71], v[134:135] op_sel_hi:[1,0]
	v_cvt_pk_fp8_f32 v122, v6, v7
	v_pk_fma_f32 v[4:5], v[4:5], v[56:57], v[12:13]
	v_pk_fma_f32 v[8:9], v[8:9], v[60:61], v[16:17]
	s_waitcnt lgkmcnt(1)
	v_pk_fma_f32 v[12:13], v[62:63], v[18:19], v[26:27]
	s_waitcnt lgkmcnt(0)
	v_pk_fma_f32 v[16:17], v[70:71], v[22:23], v[30:31]
	v_cvt_pk_fp8_f32 v123, v12, v13
	v_cvt_pk_fp8_f32 v125, v16, v17
	v_cvt_pk_fp8_f32 v120, v4, v5 op_sel:[0,0,1]
	v_pk_mul_f32 v[64:65], v[64:65], v[134:135] op_sel_hi:[1,0]
	v_pk_mul_f32 v[72:73], v[72:73], v[134:135] op_sel_hi:[1,0]
	v_cvt_pk_fp8_f32 v122, v8, v9 op_sel:[0,0,1]
	v_pk_fma_f32 v[10:11], v[64:65], v[20:21], v[28:29]
	v_pk_fma_f32 v[14:15], v[72:73], v[24:25], v[32:33]
	v_cvt_pk_f16_f32 v18, v2, v3
	v_cvt_pk_f16_f32 v19, v4, v5
	v_cvt_pk_f16_f32 v2, v6, v7
	v_cvt_pk_f16_f32 v3, v8, v9
	v_cvt_pk_f16_f32 v6, v12, v13
	v_cvt_pk_f16_f32 v7, v10, v11
	v_cvt_pk_f16_f32 v12, v16, v17
	v_cvt_pk_f16_f32 v13, v14, v15
	global_store_dwordx2 v[40:41], v[18:19], off offset:2048 nt
	v_cvt_pk_fp8_f32 v123, v10, v11 op_sel:[0,0,1]
	v_cvt_pk_fp8_f32 v125, v14, v15 op_sel:[0,0,1]
	global_store_dword v116, v120, s[16:17] offset:1024 nt
	global_store_dwordx2 v[40:41], v[2:3], off offset:2560 nt
	global_store_dword v116, v122, s[16:17] offset:1280 nt
	global_store_dwordx2 v[40:41], v[6:7], off offset:3072 nt
	global_store_dword v116, v123, s[16:17] offset:1536 nt
	global_store_dwordx2 v[40:41], v[12:13], off offset:3584 nt
	global_store_dword v116, v125, s[16:17] offset:1792 nt
	v_pk_mul_f32 v[74:75], v[74:75], v[134:135] op_sel_hi:[1,0]
	ds_read_b128 v[2:5], v1 offset:8192
	ds_read_b128 v[6:9], v1 offset:9216
	ds_read_b128 v[10:13], v1 offset:24576
	ds_read_b128 v[14:17], v1 offset:25600
	ds_read_b128 v[18:21], v1 offset:10240
	ds_read_b128 v[22:25], v1 offset:11264
	ds_read_b128 v[26:29], v1 offset:26624
	ds_read_b128 v[30:33], v1 offset:27648
	s_waitcnt lgkmcnt(5)
	v_pk_fma_f32 v[2:3], v[74:75], v[2:3], v[10:11]
	v_pk_mul_f32 v[78:79], v[78:79], v[134:135] op_sel_hi:[1,0]
	v_cvt_pk_fp8_f32 v124, v2, v3
	s_waitcnt lgkmcnt(4)
	v_pk_fma_f32 v[6:7], v[78:79], v[6:7], v[14:15]
	v_pk_mul_f32 v[76:77], v[76:77], v[134:135] op_sel_hi:[1,0]
	v_pk_mul_f32 v[80:81], v[80:81], v[134:135] op_sel_hi:[1,0]
	v_pk_mul_f32 v[82:83], v[82:83], v[134:135] op_sel_hi:[1,0]
	v_pk_mul_f32 v[86:87], v[86:87], v[134:135] op_sel_hi:[1,0]
	v_cvt_pk_fp8_f32 v126, v6, v7
	v_pk_fma_f32 v[4:5], v[76:77], v[4:5], v[12:13]
	v_pk_fma_f32 v[8:9], v[80:81], v[8:9], v[16:17]
	s_waitcnt lgkmcnt(1)
	v_pk_fma_f32 v[12:13], v[82:83], v[18:19], v[26:27]
	s_waitcnt lgkmcnt(0)
	v_pk_fma_f32 v[16:17], v[86:87], v[22:23], v[30:31]
	v_cvt_pk_fp8_f32 v127, v12, v13
	v_cvt_pk_fp8_f32 v129, v16, v17
	v_cvt_pk_fp8_f32 v124, v4, v5 op_sel:[0,0,1]
	v_pk_mul_f32 v[84:85], v[84:85], v[134:135] op_sel_hi:[1,0]
	v_pk_mul_f32 v[88:89], v[88:89], v[134:135] op_sel_hi:[1,0]
	v_cvt_pk_fp8_f32 v126, v8, v9 op_sel:[0,0,1]
	v_pk_fma_f32 v[10:11], v[84:85], v[20:21], v[28:29]
	v_pk_fma_f32 v[14:15], v[88:89], v[24:25], v[32:33]
	v_cvt_pk_f16_f32 v18, v2, v3
	v_cvt_pk_f16_f32 v19, v4, v5
	v_cvt_pk_f16_f32 v2, v6, v7
	v_cvt_pk_f16_f32 v3, v8, v9
	v_cvt_pk_f16_f32 v6, v12, v13
	v_cvt_pk_f16_f32 v7, v10, v11
	v_cvt_pk_f16_f32 v12, v16, v17
	v_cvt_pk_f16_f32 v13, v14, v15
	global_store_dwordx2 v[38:39], v[18:19], off nt
	v_cvt_pk_fp8_f32 v127, v10, v11 op_sel:[0,0,1]
	v_cvt_pk_fp8_f32 v129, v14, v15 op_sel:[0,0,1]
	global_store_dword v116, v124, s[16:17] offset:2048 nt
	global_store_dwordx2 v[38:39], v[2:3], off offset:512 nt
	global_store_dword v116, v126, s[16:17] offset:2304 nt
	global_store_dwordx2 v[38:39], v[6:7], off offset:1024 nt
	global_store_dword v116, v127, s[16:17] offset:2560 nt
	global_store_dwordx2 v[38:39], v[12:13], off offset:1536 nt
	global_store_dword v116, v129, s[16:17] offset:2816 nt
	v_pk_mul_f32 v[90:91], v[90:91], v[134:135] op_sel_hi:[1,0]
	ds_read_b128 v[2:5], v1 offset:12288
	ds_read_b128 v[6:9], v1 offset:13312
	ds_read_b128 v[10:13], v1 offset:28672
	ds_read_b128 v[14:17], v1 offset:29696
	ds_read_b128 v[18:21], v1 offset:14336
	ds_read_b128 v[22:25], v1 offset:15360
	ds_read_b128 v[26:29], v1 offset:30720
	ds_read_b128 v[30:33], v1 offset:31744
	s_waitcnt lgkmcnt(5)
	v_pk_fma_f32 v[2:3], v[90:91], v[2:3], v[10:11]
	v_pk_mul_f32 v[94:95], v[94:95], v[134:135] op_sel_hi:[1,0]
	v_cvt_pk_fp8_f32 v128, v2, v3
	s_waitcnt lgkmcnt(4)
	v_pk_fma_f32 v[6:7], v[94:95], v[6:7], v[14:15]
	v_pk_mul_f32 v[92:93], v[92:93], v[134:135] op_sel_hi:[1,0]
	v_pk_mul_f32 v[96:97], v[96:97], v[134:135] op_sel_hi:[1,0]
	v_pk_mul_f32 v[98:99], v[98:99], v[134:135] op_sel_hi:[1,0]
	v_pk_mul_f32 v[102:103], v[102:103], v[134:135] op_sel_hi:[1,0]
	v_cvt_pk_fp8_f32 v130, v6, v7
	v_pk_fma_f32 v[4:5], v[92:93], v[4:5], v[12:13]
	v_pk_fma_f32 v[8:9], v[96:97], v[8:9], v[16:17]
	s_waitcnt lgkmcnt(1)
	v_pk_fma_f32 v[12:13], v[98:99], v[18:19], v[26:27]
	s_waitcnt lgkmcnt(0)
	v_pk_fma_f32 v[16:17], v[102:103], v[22:23], v[30:31]
	v_cvt_pk_fp8_f32 v131, v12, v13
	v_cvt_pk_fp8_f32 v132, v16, v17
	v_cvt_pk_fp8_f32 v128, v4, v5 op_sel:[0,0,1]
	v_pk_mul_f32 v[100:101], v[100:101], v[134:135] op_sel_hi:[1,0]
	v_pk_mul_f32 v[104:105], v[104:105], v[134:135] op_sel_hi:[1,0]
	v_cvt_pk_fp8_f32 v130, v8, v9 op_sel:[0,0,1]
	v_pk_fma_f32 v[10:11], v[100:101], v[20:21], v[28:29]
	v_pk_fma_f32 v[14:15], v[104:105], v[24:25], v[32:33]
	v_cvt_pk_f16_f32 v18, v2, v3
	v_cvt_pk_f16_f32 v19, v4, v5
	v_cvt_pk_f16_f32 v2, v6, v7
	v_cvt_pk_f16_f32 v3, v8, v9
	v_cvt_pk_f16_f32 v6, v12, v13
	v_cvt_pk_f16_f32 v7, v10, v11
	v_cvt_pk_f16_f32 v12, v16, v17
	v_cvt_pk_f16_f32 v13, v14, v15
	global_store_dwordx2 v[38:39], v[18:19], off offset:2048 nt
	v_cvt_pk_fp8_f32 v131, v10, v11 op_sel:[0,0,1]
	v_cvt_pk_fp8_f32 v132, v14, v15 op_sel:[0,0,1]
	global_store_dword v116, v128, s[16:17] offset:3072 nt
	global_store_dwordx2 v[38:39], v[2:3], off offset:2560 nt
	global_store_dword v116, v130, s[16:17] offset:3328 nt
	global_store_dwordx2 v[38:39], v[6:7], off offset:3072 nt
	global_store_dword v116, v131, s[16:17] offset:3584 nt
	global_store_dwordx2 v[38:39], v[12:13], off offset:3584 nt
	global_store_dword v116, v132, s[16:17] offset:3840 nt
	s_add_u32 s16, s16, s30
	s_addc_u32 s17, s17, s31
	s_add_u32 s6, s6, s14
	s_addc_u32 s7, s7, s15
	s_cmpk_lt_i32 s8, 0x4000
	s_cbranch_scc1 .LBB0_1395

.LBB0_1655:
	global_load_dwordx4 v[8:11], v[4:5], off nt
	global_load_dwordx4 v[12:15], v[2:3], off nt
	v_add_u32_e32 v6, 0x200, v6
	v_cmp_lt_i32_e32 vcc, s10, v6
	v_lshl_add_u64 v[2:3], v[2:3], 0, s[4:5]
	v_lshl_add_u64 v[4:5], v[4:5], 0, s[4:5]
	s_or_b64 s[2:3], vcc, s[2:3]
	s_waitcnt vmcnt(1)
	ds_write_b128 v7, v[8:11]
	s_waitcnt vmcnt(0)
	ds_write_b128 v7, v[12:15] offset:16384
	v_add_u32_e32 v7, 0x2000, v7
	s_andn2_b64 exec, exec, s[2:3]
	s_cbranch_execnz .LBB0_1655

.LBB0_1658:
	v_cmp_lt_i32_e32 vcc, v109, v108
	v_lshl_add_u64 v[0:1], s[8:9], 0, v[32:33]
	v_lshl_add_u64 v[8:9], v[0:1], 0, s[12:13]
	v_cndmask_b32_e32 v2, v107, v109, vcc
	v_cmp_lt_i32_e32 vcc, v110, v108
	global_load_dwordx2 v[42:43], v32, s[8:9]
	global_load_dwordx2 v[44:45], v32, s[8:9] offset:512
	global_load_dwordx2 v[46:47], v32, s[8:9] offset:1024
	global_load_dwordx2 v[48:49], v32, s[8:9] offset:1536
	global_load_dwordx2 v[50:51], v32, s[8:9] offset:2048
	global_load_dwordx2 v[52:53], v32, s[8:9] offset:2560
	v_cndmask_b32_e32 v3, v107, v110, vcc
	v_cmp_lt_i32_e32 vcc, v111, v108
	global_load_dwordx2 v[54:55], v32, s[8:9] offset:3072
	global_load_dwordx2 v[56:57], v32, s[8:9] offset:3584
	v_cndmask_b32_e32 v4, v107, v111, vcc
	v_cmp_lt_i32_e32 vcc, v112, v108
	global_load_dwordx2 v[58:59], v[8:9], off offset:512 nt
	global_load_dwordx2 v[60:61], v[8:9], off offset:1024 nt
	global_load_dwordx2 v[62:63], v[8:9], off offset:1536 nt
	v_cndmask_b32_e32 v5, v107, v112, vcc
	v_cmp_lt_i32_e32 vcc, v113, v108
	v_lshlrev_b32_e32 v117, 2, v2
	v_lshlrev_b32_e32 v161, 2, v3
	v_cndmask_b32_e32 v6, v107, v113, vcc
	v_cmp_lt_i32_e32 vcc, v114, v108
	v_lshlrev_b32_e32 v164, 2, v4
	v_lshlrev_b32_e32 v165, 2, v5
	v_cndmask_b32_e32 v7, v107, v114, vcc
	v_add_co_u32_e32 v38, vcc, s3, v34
	v_lshlrev_b32_e32 v166, 2, v6
	s_nop 0
	v_addc_co_u32_e32 v39, vcc, 0, v35, vcc
	v_add_co_u32_e32 v36, vcc, s16, v34
	v_lshlrev_b32_e32 v167, 2, v7
	s_nop 0
	v_addc_co_u32_e32 v37, vcc, 0, v35, vcc
	v_add_co_u32_e32 v40, vcc, s17, v34
	s_add_i32 s2, s2, s4
	s_nop 0
	v_addc_co_u32_e32 v41, vcc, 0, v35, vcc
	v_add_co_u32_e32 v10, vcc, s3, v0
	s_add_u32 s8, s8, s10
	s_nop 0
	v_addc_co_u32_e32 v11, vcc, 0, v1, vcc
	global_load_dwordx2 v[64:65], v[8:9], off offset:2048 nt
	global_load_dwordx2 v[66:67], v[8:9], off offset:2560 nt
	global_load_dwordx2 v[68:69], v[8:9], off offset:3072 nt
	global_load_dwordx2 v[70:71], v[10:11], off offset:512 nt
	global_load_dwordx2 v[72:73], v[10:11], off offset:1024 nt
	global_load_dwordx2 v[74:75], v[10:11], off offset:1536 nt
	global_load_dwordx2 v[76:77], v[10:11], off offset:2048 nt
	global_load_dwordx2 v[78:79], v[10:11], off offset:2560 nt
	global_load_dwordx2 v[80:81], v[10:11], off offset:3072 nt
	global_load_dwordx2 v[82:83], v[10:11], off offset:3584 nt
	v_add_co_u32_e32 v0, vcc, s5, v0
	s_addc_u32 s9, s9, s11
	s_nop 0
	v_addc_co_u32_e32 v1, vcc, 0, v1, vcc
	global_load_dwordx2 v[84:85], v[10:11], off nt
	global_load_dwordx2 v[86:87], v[8:9], off offset:3584 nt
	global_load_dwordx2 v[88:89], v[0:1], off offset:-4096 nt
	global_load_dwordx2 v[90:91], v[0:1], off nt
	global_load_dwordx2 v[92:93], v[0:1], off offset:512 nt
	global_load_dwordx2 v[94:95], v[0:1], off offset:1024 nt
	global_load_dwordx2 v[96:97], v[0:1], off offset:1536 nt
	global_load_dwordx2 v[98:99], v[0:1], off offset:2048 nt
	global_load_dwordx2 v[100:101], v[0:1], off offset:2560 nt
	global_load_dwordx2 v[102:103], v[0:1], off offset:3072 nt
	global_load_dwordx2 v[104:105], v[0:1], off offset:3584 nt
	ds_read_b128 v[8:11], v106
	ds_read_b128 v[0:3], v106 offset:1024
	ds_read_b128 v[24:27], v106 offset:16384
	ds_read_b128 v[16:19], v106 offset:17408
	ds_read_b128 v[12:15], v106 offset:2048
	ds_read_b128 v[4:7], v106 offset:3072
	ds_read_b128 v[28:31], v106 offset:18432
	ds_read_b128 v[20:23], v106 offset:19456
	s_cmpk_lt_i32 s2, 0x4000
	s_waitcnt vmcnt(31)
	v_lshlrev_b32_e32 v118, 16, v42
	v_and_b32_e32 v119, 0xffff0000, v42
	v_lshlrev_b32_e32 v120, 16, v43
	s_waitcnt vmcnt(28)
	v_lshlrev_b32_e32 v126, 16, v48
	v_and_b32_e32 v127, 0xffff0000, v48
	v_lshlrev_b32_e32 v128, 16, v49
	v_and_b32_e32 v129, 0xffff0000, v49
	v_and_b32_e32 v121, 0xffff0000, v43
	v_lshlrev_b32_e32 v42, 16, v44
	v_and_b32_e32 v43, 0xffff0000, v44
	v_lshlrev_b32_e32 v44, 16, v45
	v_and_b32_e32 v45, 0xffff0000, v45
	v_lshlrev_b32_e32 v122, 16, v46
	v_and_b32_e32 v123, 0xffff0000, v46
	v_lshlrev_b32_e32 v124, 16, v47
	v_and_b32_e32 v125, 0xffff0000, v47
	s_waitcnt vmcnt(27)
	v_lshlrev_b32_e32 v130, 16, v50
	v_and_b32_e32 v131, 0xffff0000, v50
	v_lshlrev_b32_e32 v132, 16, v51
	v_and_b32_e32 v133, 0xffff0000, v51
	s_waitcnt vmcnt(26)
	v_lshlrev_b32_e32 v134, 16, v52
	v_and_b32_e32 v135, 0xffff0000, v52
	v_lshlrev_b32_e32 v136, 16, v53
	v_and_b32_e32 v137, 0xffff0000, v53
	s_waitcnt vmcnt(25)
	v_lshlrev_b32_e32 v138, 16, v54
	v_and_b32_e32 v139, 0xffff0000, v54
	v_lshlrev_b32_e32 v140, 16, v55
	v_and_b32_e32 v141, 0xffff0000, v55
	s_waitcnt vmcnt(24)
	v_lshlrev_b32_e32 v142, 16, v56
	v_and_b32_e32 v143, 0xffff0000, v56
	v_lshlrev_b32_e32 v144, 16, v57
	v_and_b32_e32 v145, 0xffff0000, v57
	s_waitcnt vmcnt(21)
	v_fma_mix_f32 v50, v62, s14, v126 op_sel_hi:[1,0,0]
	v_fma_mix_f32 v51, v62, s14, v127 op_sel:[1,0,0] op_sel_hi:[1,0,0]
	v_fma_mix_f32 v52, v63, s14, v128 op_sel_hi:[1,0,0]
	v_fma_mix_f32 v53, v63, s14, v129 op_sel:[1,0,0] op_sel_hi:[1,0,0]
	v_fma_mix_f32 v42, v58, s14, v42 op_sel_hi:[1,0,0]
	v_fma_mix_f32 v43, v58, s14, v43 op_sel:[1,0,0] op_sel_hi:[1,0,0]
	v_fma_mix_f32 v44, v59, s14, v44 op_sel_hi:[1,0,0]
	v_fma_mix_f32 v45, v59, s14, v45 op_sel:[1,0,0] op_sel_hi:[1,0,0]
	v_fma_mix_f32 v46, v60, s14, v122 op_sel_hi:[1,0,0]
	v_fma_mix_f32 v47, v60, s14, v123 op_sel:[1,0,0] op_sel_hi:[1,0,0]
	v_fma_mix_f32 v48, v61, s14, v124 op_sel_hi:[1,0,0]
	v_fma_mix_f32 v49, v61, s14, v125 op_sel:[1,0,0] op_sel_hi:[1,0,0]
	s_waitcnt vmcnt(20)
	v_fma_mix_f32 v54, v64, s14, v130 op_sel_hi:[1,0,0]
	v_fma_mix_f32 v55, v64, s14, v131 op_sel:[1,0,0] op_sel_hi:[1,0,0]
	v_fma_mix_f32 v58, v65, s14, v132 op_sel_hi:[1,0,0]
	v_fma_mix_f32 v59, v65, s14, v133 op_sel:[1,0,0] op_sel_hi:[1,0,0]
	s_waitcnt vmcnt(19)
	v_fma_mix_f32 v56, v66, s14, v134 op_sel_hi:[1,0,0]
	v_fma_mix_f32 v57, v66, s14, v135 op_sel:[1,0,0] op_sel_hi:[1,0,0]
	v_fma_mix_f32 v62, v67, s14, v136 op_sel_hi:[1,0,0]
	v_fma_mix_f32 v63, v67, s14, v137 op_sel:[1,0,0] op_sel_hi:[1,0,0]
	s_waitcnt vmcnt(18)
	v_fma_mix_f32 v60, v68, s14, v138 op_sel_hi:[1,0,0]
	v_fma_mix_f32 v61, v68, s14, v139 op_sel:[1,0,0] op_sel_hi:[1,0,0]
	v_fma_mix_f32 v64, v69, s14, v140 op_sel_hi:[1,0,0]
	v_fma_mix_f32 v65, v69, s14, v141 op_sel:[1,0,0] op_sel_hi:[1,0,0]
	v_add_f32_e32 v126, v50, v51
	v_add_f32_e32 v127, v52, v53
	s_waitcnt vmcnt(9)
	v_fma_mix_f32 v66, v86, s14, v142 op_sel_hi:[1,0,0]
	v_fma_mix_f32 v67, v86, s14, v143 op_sel:[1,0,0] op_sel_hi:[1,0,0]
	v_fma_mix_f32 v68, v87, s14, v144 op_sel_hi:[1,0,0]
	v_fma_mix_f32 v69, v87, s14, v145 op_sel:[1,0,0] op_sel_hi:[1,0,0]
	v_lshlrev_b32_e32 v86, 16, v84
	v_and_b32_e32 v87, 0xffff0000, v84
	v_lshlrev_b32_e32 v134, 16, v85
	v_and_b32_e32 v135, 0xffff0000, v85
	v_lshlrev_b32_e32 v156, 16, v80
	v_and_b32_e32 v157, 0xffff0000, v80
	v_lshlrev_b32_e32 v158, 16, v81
	v_and_b32_e32 v159, 0xffff0000, v81
	s_waitcnt vmcnt(8)
	v_fma_mix_f32 v80, v88, s14, v118 op_sel_hi:[1,0,0]
	v_fma_mix_f32 v81, v88, s14, v119 op_sel:[1,0,0] op_sel_hi:[1,0,0]
	v_fma_mix_f32 v84, v89, s14, v120 op_sel_hi:[1,0,0]
	v_fma_mix_f32 v85, v89, s14, v121 op_sel:[1,0,0] op_sel_hi:[1,0,0]
	v_add_f32_e32 v120, v126, v127
	v_add_f32_e32 v126, v80, v81
	v_add_f32_e32 v127, v84, v85
	v_add_f32_e32 v122, v42, v43
	v_add_f32_e32 v123, v44, v45
	v_add_f32_e32 v126, v126, v127
	v_add_f32_e32 v124, v46, v47
	v_add_f32_e32 v125, v48, v49
	v_add_f32_e32 v118, v122, v123
	v_add_f32_e32 v126, 0, v126
	v_add_f32_e32 v119, v124, v125
	v_add_f32_e32 v118, v126, v118
	v_add_f32_e32 v128, v54, v55
	v_add_f32_e32 v129, v58, v59
	v_add_f32_e32 v118, v118, v119
	v_add_f32_e32 v130, v56, v57
	v_add_f32_e32 v131, v62, v63
	v_add_f32_e32 v121, v128, v129
	v_add_f32_e32 v118, v118, v120
	v_add_f32_e32 v132, v60, v61
	v_add_f32_e32 v133, v64, v65
	v_add_f32_e32 v122, v130, v131
	v_add_f32_e32 v118, v118, v121
	v_lshlrev_b32_e32 v136, 16, v70
	v_and_b32_e32 v137, 0xffff0000, v70
	v_lshlrev_b32_e32 v138, 16, v71
	v_and_b32_e32 v139, 0xffff0000, v71
	v_lshlrev_b32_e32 v144, 16, v74
	v_and_b32_e32 v145, 0xffff0000, v74
	v_lshlrev_b32_e32 v146, 16, v75
	v_and_b32_e32 v147, 0xffff0000, v75
	v_add_f32_e32 v123, v132, v133
	v_add_f32_e32 v124, v66, v67
	v_add_f32_e32 v125, v68, v69
	s_waitcnt vmcnt(7)
	v_fma_mix_f32 v70, v90, s14, v86 op_sel_hi:[1,0,0]
	v_fma_mix_f32 v71, v90, s14, v87 op_sel:[1,0,0] op_sel_hi:[1,0,0]
	v_fma_mix_f32 v74, v91, s14, v134 op_sel_hi:[1,0,0]
	v_fma_mix_f32 v75, v91, s14, v135 op_sel:[1,0,0] op_sel_hi:[1,0,0]
	v_add_f32_e32 v118, v118, v122
	v_lshlrev_b32_e32 v140, 16, v72
	v_and_b32_e32 v141, 0xffff0000, v72
	v_lshlrev_b32_e32 v142, 16, v73
	v_and_b32_e32 v143, 0xffff0000, v73
	v_lshlrev_b32_e32 v152, 16, v78
	v_and_b32_e32 v153, 0xffff0000, v78
	v_lshlrev_b32_e32 v154, 16, v79
	v_and_b32_e32 v155, 0xffff0000, v79
	s_waitcnt vmcnt(6)
	v_fma_mix_f32 v72, v92, s14, v136 op_sel_hi:[1,0,0]
	v_fma_mix_f32 v73, v92, s14, v137 op_sel:[1,0,0] op_sel_hi:[1,0,0]
	v_fma_mix_f32 v78, v93, s14, v138 op_sel_hi:[1,0,0]
	v_fma_mix_f32 v79, v93, s14, v139 op_sel:[1,0,0] op_sel_hi:[1,0,0]
	v_add_f32_e32 v124, v124, v125
	v_add_f32_e32 v125, v70, v71
	v_add_f32_e32 v128, v74, v75
	v_add_f32_e32 v118, v118, v123
	v_lshlrev_b32_e32 v148, 16, v76
	v_and_b32_e32 v149, 0xffff0000, v76
	v_lshlrev_b32_e32 v150, 16, v77
	v_and_b32_e32 v151, 0xffff0000, v77
	s_waitcnt vmcnt(5)
	v_fma_mix_f32 v76, v94, s14, v140 op_sel_hi:[1,0,0]
	v_fma_mix_f32 v77, v94, s14, v141 op_sel:[1,0,0] op_sel_hi:[1,0,0]
	v_fma_mix_f32 v86, v95, s14, v142 op_sel_hi:[1,0,0]
	v_fma_mix_f32 v87, v95, s14, v143 op_sel:[1,0,0] op_sel_hi:[1,0,0]
	v_add_f32_e32 v129, v72, v73
	v_add_f32_e32 v130, v78, v79
	v_add_f32_e32 v125, v125, v128
	v_add_f32_e32 v118, v118, v124
	v_lshlrev_b32_e32 v160, 16, v82
	v_and_b32_e32 v162, 0xffff0000, v82
	v_lshlrev_b32_e32 v163, 16, v83
	v_and_b32_e32 v168, 0xffff0000, v83
	s_waitcnt vmcnt(4)
	v_fma_mix_f32 v82, v96, s14, v144 op_sel_hi:[1,0,0]
	v_fma_mix_f32 v83, v96, s14, v145 op_sel:[1,0,0] op_sel_hi:[1,0,0]
	v_fma_mix_f32 v90, v97, s14, v146 op_sel_hi:[1,0,0]
	v_fma_mix_f32 v91, v97, s14, v147 op_sel:[1,0,0] op_sel_hi:[1,0,0]
	v_add_f32_e32 v131, v76, v77
	v_add_f32_e32 v132, v86, v87
	v_add_f32_e32 v127, v129, v130
	v_add_f32_e32 v118, v118, v125
	s_waitcnt vmcnt(3)
	v_fma_mix_f32 v88, v98, s14, v148 op_sel_hi:[1,0,0]
	v_fma_mix_f32 v89, v98, s14, v149 op_sel:[1,0,0] op_sel_hi:[1,0,0]
	v_fma_mix_f32 v94, v99, s14, v150 op_sel_hi:[1,0,0]
	v_fma_mix_f32 v95, v99, s14, v151 op_sel:[1,0,0] op_sel_hi:[1,0,0]
	v_add_f32_e32 v133, v82, v83
	v_add_f32_e32 v134, v90, v91
	v_add_f32_e32 v128, v131, v132
	v_add_f32_e32 v118, v118, v127
	s_waitcnt vmcnt(2)
	v_fma_mix_f32 v92, v100, s14, v152 op_sel_hi:[1,0,0]
	v_fma_mix_f32 v93, v100, s14, v153 op_sel:[1,0,0] op_sel_hi:[1,0,0]
	v_fma_mix_f32 v98, v101, s14, v154 op_sel_hi:[1,0,0]
	v_fma_mix_f32 v99, v101, s14, v155 op_sel:[1,0,0] op_sel_hi:[1,0,0]
	v_add_f32_e32 v135, v88, v89
	v_add_f32_e32 v136, v94, v95
	v_add_f32_e32 v129, v133, v134
	v_add_f32_e32 v118, v118, v128
	s_waitcnt vmcnt(1)
	v_fma_mix_f32 v96, v102, s14, v156 op_sel_hi:[1,0,0]
	v_fma_mix_f32 v97, v102, s14, v157 op_sel:[1,0,0] op_sel_hi:[1,0,0]
	v_fma_mix_f32 v102, v103, s14, v158 op_sel_hi:[1,0,0]
	v_fma_mix_f32 v103, v103, s14, v159 op_sel:[1,0,0] op_sel_hi:[1,0,0]
	v_add_f32_e32 v137, v92, v93
	v_add_f32_e32 v138, v98, v99
	v_add_f32_e32 v130, v135, v136
	v_add_f32_e32 v118, v118, v129
	s_waitcnt vmcnt(0)
	v_fma_mix_f32 v100, v104, s14, v160 op_sel_hi:[1,0,0]
	v_fma_mix_f32 v101, v104, s14, v162 op_sel:[1,0,0] op_sel_hi:[1,0,0]
	v_fma_mix_f32 v104, v105, s14, v163 op_sel_hi:[1,0,0]
	v_fma_mix_f32 v105, v105, s14, v168 op_sel:[1,0,0] op_sel_hi:[1,0,0]
	v_add_f32_e32 v139, v96, v97
	v_add_f32_e32 v140, v102, v103
	v_add_f32_e32 v131, v137, v138
	v_add_f32_e32 v118, v118, v130
	v_add_f32_e32 v141, v100, v101
	v_add_f32_e32 v142, v104, v105
	v_add_f32_e32 v132, v139, v140
	v_add_f32_e32 v118, v118, v131
	v_add_f32_e32 v133, v141, v142
	v_add_f32_e32 v118, v118, v132
	v_add_f32_e32 v118, v118, v133
	ds_bpermute_b32 v119, v117, v118
	s_waitcnt lgkmcnt(0)
	v_add_f32_e32 v118, v118, v119
	ds_bpermute_b32 v119, v161, v118
	s_waitcnt lgkmcnt(0)
	v_add_f32_e32 v118, v118, v119
	ds_bpermute_b32 v119, v164, v118
	s_waitcnt lgkmcnt(0)
	v_add_f32_e32 v118, v118, v119
	ds_bpermute_b32 v119, v165, v118
	s_waitcnt lgkmcnt(0)
	v_add_f32_e32 v118, v118, v119
	ds_bpermute_b32 v119, v166, v118
	s_waitcnt lgkmcnt(0)
	v_add_f32_e32 v118, v118, v119
	ds_bpermute_b32 v119, v167, v118
	s_waitcnt lgkmcnt(0)
	v_add_f32_e32 v118, v118, v119
	v_fmac_f32_e32 v81, 0xb9800000, v118
	v_fmac_f32_e32 v80, 0xb9800000, v118
	v_fmac_f32_e32 v85, 0xb9800000, v118
	v_fmac_f32_e32 v84, 0xb9800000, v118
	v_fmac_f32_e32 v43, 0xb9800000, v118
	v_fmac_f32_e32 v42, 0xb9800000, v118
	v_fmac_f32_e32 v45, 0xb9800000, v118
	v_fmac_f32_e32 v44, 0xb9800000, v118
	v_fmac_f32_e32 v47, 0xb9800000, v118
	v_fmac_f32_e32 v46, 0xb9800000, v118
	v_fmac_f32_e32 v49, 0xb9800000, v118
	v_fmac_f32_e32 v48, 0xb9800000, v118
	v_fmac_f32_e32 v53, 0xb9800000, v118
	v_fmac_f32_e32 v52, 0xb9800000, v118
	v_fmac_f32_e32 v51, 0xb9800000, v118
	v_fmac_f32_e32 v50, 0xb9800000, v118
	v_fmac_f32_e32 v55, 0xb9800000, v118
	v_fmac_f32_e32 v54, 0xb9800000, v118
	v_fmac_f32_e32 v59, 0xb9800000, v118
	v_fmac_f32_e32 v58, 0xb9800000, v118
	v_fmac_f32_e32 v57, 0xb9800000, v118
	v_fmac_f32_e32 v56, 0xb9800000, v118
	v_fmac_f32_e32 v63, 0xb9800000, v118
	v_fmac_f32_e32 v62, 0xb9800000, v118
	v_fmac_f32_e32 v65, 0xb9800000, v118
	v_fmac_f32_e32 v64, 0xb9800000, v118
	v_fmac_f32_e32 v61, 0xb9800000, v118
	v_fmac_f32_e32 v60, 0xb9800000, v118
	v_fmac_f32_e32 v67, 0xb9800000, v118
	v_fmac_f32_e32 v66, 0xb9800000, v118
	v_fmac_f32_e32 v69, 0xb9800000, v118
	v_fmac_f32_e32 v68, 0xb9800000, v118
	v_fmac_f32_e32 v71, 0xb9800000, v118
	v_fmac_f32_e32 v70, 0xb9800000, v118
	v_fmac_f32_e32 v75, 0xb9800000, v118
	v_fmac_f32_e32 v74, 0xb9800000, v118
	v_fmac_f32_e32 v79, 0xb9800000, v118
	v_fmac_f32_e32 v78, 0xb9800000, v118
	v_fmac_f32_e32 v73, 0xb9800000, v118
	v_fmac_f32_e32 v72, 0xb9800000, v118
	v_fmac_f32_e32 v77, 0xb9800000, v118
	v_fmac_f32_e32 v76, 0xb9800000, v118
	v_fmac_f32_e32 v87, 0xb9800000, v118
	v_fmac_f32_e32 v86, 0xb9800000, v118
	v_fmac_f32_e32 v83, 0xb9800000, v118
	v_fmac_f32_e32 v82, 0xb9800000, v118
	v_fmac_f32_e32 v91, 0xb9800000, v118
	v_fmac_f32_e32 v90, 0xb9800000, v118
	v_fmac_f32_e32 v95, 0xb9800000, v118
	v_fmac_f32_e32 v94, 0xb9800000, v118
	v_fmac_f32_e32 v89, 0xb9800000, v118
	v_fmac_f32_e32 v88, 0xb9800000, v118
	v_fmac_f32_e32 v93, 0xb9800000, v118
	v_fmac_f32_e32 v92, 0xb9800000, v118
	v_fmac_f32_e32 v99, 0xb9800000, v118
	v_fmac_f32_e32 v98, 0xb9800000, v118
	v_fmac_f32_e32 v97, 0xb9800000, v118
	v_fmac_f32_e32 v96, 0xb9800000, v118
	v_fmac_f32_e32 v103, 0xb9800000, v118
	v_fmac_f32_e32 v102, 0xb9800000, v118
	v_fmac_f32_e32 v105, 0xb9800000, v118
	v_fmac_f32_e32 v104, 0xb9800000, v118
	v_fmac_f32_e32 v101, 0xb9800000, v118
	v_fmac_f32_e32 v100, 0xb9800000, v118
	v_pk_mul_f32 v[118:119], v[84:85], v[84:85]
	v_pk_mul_f32 v[120:121], v[80:81], v[80:81]
	v_pk_mul_f32 v[122:123], v[44:45], v[44:45]
	v_pk_mul_f32 v[124:125], v[42:43], v[42:43]
	v_pk_mov_b32 v[162:163], v[120:121], v[118:119] op_sel:[1,0]
	v_mov_b32_e32 v121, v119
	v_pk_mov_b32 v[118:119], v[124:125], v[122:123] op_sel:[1,0]
	v_mov_b32_e32 v125, v123
	v_mul_f32_e32 v126, v46, v46
	v_mul_f32_e32 v128, v48, v48
	v_pk_add_f32 v[120:121], v[162:163], v[120:121]
	v_pk_add_f32 v[118:119], v[118:119], v[124:125]
	v_pk_fma_f32 v[122:123], v[46:47], v[46:47], v[126:127] op_sel_hi:[1,1,0]
	v_pk_fma_f32 v[126:127], v[48:49], v[48:49], v[128:129] op_sel_hi:[1,1,0]
	v_pk_add_f32 v[120:121], v[120:121], v[120:121] op_sel_hi:[0,1]
	v_pk_add_f32 v[118:119], v[118:119], v[118:119] op_sel_hi:[0,1]
	v_pk_mul_f32 v[130:131], v[58:59], v[58:59]
	v_pk_mul_f32 v[132:133], v[54:55], v[54:55]
	v_mul_f32_e32 v122, v50, v50
	v_mul_f32_e32 v126, v51, v51
	v_mul_f32_e32 v120, v52, v52
	v_mul_f32_e32 v118, v53, v53
	v_pk_mov_b32 v[128:129], v[132:133], v[130:131] op_sel:[1,0]
	v_mov_b32_e32 v133, v131
	v_pk_add_f32 v[122:123], v[122:123], v[126:127]
	v_pk_add_f32 v[118:119], v[120:121], v[118:119]
	v_mul_f32_e32 v134, v56, v56
	v_mul_f32_e32 v136, v62, v62
	v_pk_add_f32 v[124:125], v[128:129], v[132:133]
	v_pk_add_f32 v[118:119], v[122:123], v[118:119]
	v_pk_fma_f32 v[130:131], v[56:57], v[56:57], v[134:135] op_sel_hi:[1,1,0]
	v_pk_fma_f32 v[134:135], v[62:63], v[62:63], v[136:137] op_sel_hi:[1,1,0]
	v_pk_add_f32 v[124:125], v[124:125], v[124:125] op_sel_hi:[0,1]
	v_pk_add_f32 v[118:119], v[118:119], v[118:119] op_sel_hi:[0,1]
	v_pk_mul_f32 v[138:139], v[68:69], v[68:69]
	v_pk_mul_f32 v[140:141], v[66:67], v[66:67]
	v_mul_f32_e32 v130, v60, v60
	v_mul_f32_e32 v134, v61, v61
	v_mul_f32_e32 v124, v64, v64
	v_mul_f32_e32 v118, v65, v65
	v_pk_mov_b32 v[136:137], v[140:141], v[138:139] op_sel:[1,0]
	v_mov_b32_e32 v141, v139
	v_pk_add_f32 v[126:127], v[130:131], v[134:135]
	v_pk_add_f32 v[118:119], v[124:125], v[118:119]
	v_mul_f32_e32 v142, v70, v70
	v_mul_f32_e32 v144, v74, v74
	v_pk_add_f32 v[128:129], v[136:137], v[140:141]
	v_pk_add_f32 v[118:119], v[126:127], v[118:119]
	v_pk_fma_f32 v[138:139], v[70:71], v[70:71], v[142:143] op_sel_hi:[1,1,0]
	v_pk_fma_f32 v[142:143], v[74:75], v[74:75], v[144:145] op_sel_hi:[1,1,0]
	v_pk_add_f32 v[128:129], v[128:129], v[128:129] op_sel_hi:[0,1]
	v_pk_add_f32 v[118:119], v[118:119], v[118:119] op_sel_hi:[0,1]
	v_pk_mul_f32 v[146:147], v[86:87], v[86:87]
	v_pk_mul_f32 v[148:149], v[76:77], v[76:77]
	v_mul_f32_e32 v138, v72, v72
	v_mul_f32_e32 v142, v73, v73
	v_mul_f32_e32 v128, v78, v78
	v_mul_f32_e32 v118, v79, v79
	v_pk_mov_b32 v[144:145], v[148:149], v[146:147] op_sel:[1,0]
	v_mov_b32_e32 v149, v147
	v_pk_add_f32 v[130:131], v[138:139], v[142:143]
	v_pk_add_f32 v[118:119], v[128:129], v[118:119]
	v_mul_f32_e32 v150, v82, v82
	v_mul_f32_e32 v152, v90, v90
	v_pk_add_f32 v[132:133], v[144:145], v[148:149]
	v_pk_add_f32 v[118:119], v[130:131], v[118:119]
	v_pk_fma_f32 v[146:147], v[82:83], v[82:83], v[150:151] op_sel_hi:[1,1,0]
	v_pk_fma_f32 v[150:151], v[90:91], v[90:91], v[152:153] op_sel_hi:[1,1,0]
	v_pk_add_f32 v[132:133], v[132:133], v[132:133] op_sel_hi:[0,1]
	v_pk_add_f32 v[118:119], v[118:119], v[118:119] op_sel_hi:[0,1]
	v_pk_mul_f32 v[154:155], v[98:99], v[98:99]
	v_pk_mul_f32 v[156:157], v[92:93], v[92:93]
	v_mul_f32_e32 v146, v88, v88
	v_mul_f32_e32 v150, v89, v89
	v_mul_f32_e32 v132, v94, v94
	v_mul_f32_e32 v118, v95, v95
	v_pk_mov_b32 v[152:153], v[156:157], v[154:155] op_sel:[1,0]
	v_mov_b32_e32 v157, v155
	v_pk_add_f32 v[134:135], v[146:147], v[150:151]
	v_pk_add_f32 v[118:119], v[132:133], v[118:119]
	v_mul_f32_e32 v158, v96, v96
	v_mul_f32_e32 v160, v102, v102
	v_pk_add_f32 v[136:137], v[152:153], v[156:157]
	v_pk_add_f32 v[118:119], v[134:135], v[118:119]
	v_pk_fma_f32 v[154:155], v[96:97], v[96:97], v[158:159] op_sel_hi:[1,1,0]
	v_pk_fma_f32 v[158:159], v[102:103], v[102:103], v[160:161] op_sel_hi:[1,1,0]
	v_pk_add_f32 v[136:137], v[136:137], v[136:137] op_sel_hi:[0,1]
	v_pk_add_f32 v[118:119], v[118:119], v[118:119] op_sel_hi:[0,1]
	v_mul_f32_e32 v154, v100, v100
	v_mul_f32_e32 v158, v101, v101
	v_mul_f32_e32 v136, v104, v104
	v_mul_f32_e32 v118, v105, v105
	v_pk_add_f32 v[138:139], v[154:155], v[158:159]
	v_pk_add_f32 v[118:119], v[136:137], v[118:119]
	s_nop 0
	v_pk_add_f32 v[118:119], v[138:139], v[118:119]
	s_nop 0
	v_add_f32_e32 v118, v118, v119
	ds_bpermute_b32 v117, v117, v118
	s_waitcnt lgkmcnt(0)
	v_add_f32_e32 v117, v118, v117
	ds_bpermute_b32 v118, v161, v117
	s_waitcnt lgkmcnt(0)
	v_add_f32_e32 v117, v117, v118
	ds_bpermute_b32 v118, v164, v117
	s_waitcnt lgkmcnt(0)
	v_add_f32_e32 v117, v117, v118
	ds_bpermute_b32 v118, v165, v117
	s_waitcnt lgkmcnt(0)
	v_add_f32_e32 v117, v117, v118
	ds_bpermute_b32 v118, v166, v117
	s_waitcnt lgkmcnt(0)
	v_add_f32_e32 v117, v117, v118
	ds_bpermute_b32 v118, v167, v117
	s_waitcnt lgkmcnt(0)
	v_add_f32_e32 v117, v117, v118
	v_fmamk_f32 v117, v117, 0x39800000, v115
	v_mul_f32_e32 v118, 0x4f800000, v117
	v_cmp_gt_f32_e32 vcc, s15, v117
	s_nop 1
	v_cndmask_b32_e32 v117, v117, v118, vcc
	v_sqrt_f32_e32 v118, v117
	s_nop 0
	v_add_u32_e32 v119, -1, v118
	v_add_u32_e32 v120, 1, v118
	v_fma_f32 v121, -v119, v118, v117
	v_fma_f32 v122, -v120, v118, v117
	v_cmp_ge_f32_e64 s[0:1], 0, v121
	s_nop 1
	v_cndmask_b32_e64 v118, v118, v119, s[0:1]
	v_cmp_lt_f32_e64 s[0:1], 0, v122
	s_nop 1
	v_cndmask_b32_e64 v118, v118, v120, s[0:1]
	v_mul_f32_e32 v119, 0x37800000, v118
	v_cndmask_b32_e32 v118, v118, v119, vcc
	v_cmp_class_f32_e32 vcc, v117, v116
	s_nop 1
	v_cndmask_b32_e32 v117, v118, v117, vcc
	v_div_scale_f32 v118, s[0:1], v117, v117, 1.0
	v_rcp_f32_e32 v120, v118
	v_div_scale_f32 v119, vcc, 1.0, v117, 1.0
	v_fma_f32 v121, -v118, v120, 1.0
	v_fmac_f32_e32 v120, v121, v120
	v_mul_f32_e32 v121, v119, v120
	v_fma_f32 v122, -v118, v121, v119
	v_fmac_f32_e32 v121, v122, v120
	v_fma_f32 v118, -v118, v121, v119
	v_div_fmas_f32 v118, v118, v120, v121
	v_div_fixup_f32 v118, v118, v117, 1.0
	v_pk_mul_f32 v[80:81], v[80:81], v[118:119] op_sel_hi:[1,0]
	v_pk_mul_f32 v[84:85], v[84:85], v[118:119] op_sel_hi:[1,0]
	v_pk_mul_f32 v[42:43], v[42:43], v[118:119] op_sel_hi:[1,0]
	v_pk_mul_f32 v[44:45], v[44:45], v[118:119] op_sel_hi:[1,0]
	v_pk_mul_f32 v[46:47], v[46:47], v[118:119] op_sel_hi:[1,0]
	v_pk_mul_f32 v[48:49], v[48:49], v[118:119] op_sel_hi:[1,0]
	v_pk_mul_f32 v[50:51], v[50:51], v[118:119] op_sel_hi:[1,0]
	v_pk_mul_f32 v[52:53], v[52:53], v[118:119] op_sel_hi:[1,0]
	v_pk_fma_f32 v[10:11], v[10:11], v[84:85], v[26:27]
	v_pk_fma_f32 v[8:9], v[8:9], v[80:81], v[24:25]
	v_pk_fma_f32 v[2:3], v[2:3], v[44:45], v[18:19]
	v_pk_fma_f32 v[0:1], v[0:1], v[42:43], v[16:17]
	v_pk_fma_f32 v[14:15], v[14:15], v[48:49], v[30:31]
	v_pk_fma_f32 v[12:13], v[12:13], v[46:47], v[28:29]
	v_pk_fma_f32 v[6:7], v[6:7], v[52:53], v[22:23]
	v_pk_fma_f32 v[4:5], v[4:5], v[50:51], v[20:21]
	global_store_dwordx4 v[34:35], v[8:11], off nt
	global_store_dwordx4 v[34:35], v[0:3], off offset:1024 nt
	global_store_dwordx4 v[34:35], v[12:15], off offset:2048 nt
	global_store_dwordx4 v[34:35], v[4:7], off offset:3072 nt
	ds_read_b128 v[0:3], v106 offset:4096
	ds_read_b128 v[4:7], v106 offset:5120
	ds_read_b128 v[8:11], v106 offset:20480
	ds_read_b128 v[12:15], v106 offset:21504
	ds_read_b128 v[16:19], v106 offset:6144
	ds_read_b128 v[20:23], v106 offset:7168
	ds_read_b128 v[24:27], v106 offset:22528
	ds_read_b128 v[28:31], v106 offset:23552
	v_pk_mul_f32 v[58:59], v[58:59], v[118:119] op_sel_hi:[1,0]
	v_pk_mul_f32 v[54:55], v[54:55], v[118:119] op_sel_hi:[1,0]
	v_pk_mul_f32 v[62:63], v[62:63], v[118:119] op_sel_hi:[1,0]
	v_pk_mul_f32 v[56:57], v[56:57], v[118:119] op_sel_hi:[1,0]
	v_pk_mul_f32 v[64:65], v[64:65], v[118:119] op_sel_hi:[1,0]
	v_pk_mul_f32 v[60:61], v[60:61], v[118:119] op_sel_hi:[1,0]
	v_pk_mul_f32 v[68:69], v[68:69], v[118:119] op_sel_hi:[1,0]
	v_pk_mul_f32 v[66:67], v[66:67], v[118:119] op_sel_hi:[1,0]
	s_waitcnt lgkmcnt(5)
	v_pk_fma_f32 v[0:1], v[0:1], v[54:55], v[8:9]
	v_pk_fma_f32 v[2:3], v[2:3], v[58:59], v[10:11]
	s_waitcnt lgkmcnt(4)
	v_pk_fma_f32 v[4:5], v[4:5], v[56:57], v[12:13]
	v_pk_fma_f32 v[6:7], v[6:7], v[62:63], v[14:15]
	s_waitcnt lgkmcnt(1)
	v_pk_fma_f32 v[8:9], v[16:17], v[60:61], v[24:25]
	v_pk_fma_f32 v[10:11], v[18:19], v[64:65], v[26:27]
	s_waitcnt lgkmcnt(0)
	v_pk_fma_f32 v[12:13], v[20:21], v[66:67], v[28:29]
	v_pk_fma_f32 v[14:15], v[22:23], v[68:69], v[30:31]
	global_store_dwordx4 v[36:37], v[0:3], off offset:-4096 nt
	global_store_dwordx4 v[38:39], v[4:7], off offset:1024 nt
	global_store_dwordx4 v[38:39], v[8:11], off offset:2048 nt
	global_store_dwordx4 v[38:39], v[12:15], off offset:3072 nt
	ds_read_b128 v[0:3], v106 offset:8192
	ds_read_b128 v[4:7], v106 offset:9216
	ds_read_b128 v[8:11], v106 offset:24576
	ds_read_b128 v[12:15], v106 offset:25600
	ds_read_b128 v[16:19], v106 offset:10240
	ds_read_b128 v[20:23], v106 offset:11264
	ds_read_b128 v[24:27], v106 offset:26624
	ds_read_b128 v[28:31], v106 offset:27648
	v_pk_mul_f32 v[74:75], v[74:75], v[118:119] op_sel_hi:[1,0]
	v_pk_mul_f32 v[70:71], v[70:71], v[118:119] op_sel_hi:[1,0]
	v_pk_mul_f32 v[78:79], v[78:79], v[118:119] op_sel_hi:[1,0]
	v_pk_mul_f32 v[72:73], v[72:73], v[118:119] op_sel_hi:[1,0]
	v_pk_mul_f32 v[86:87], v[86:87], v[118:119] op_sel_hi:[1,0]
	v_pk_mul_f32 v[76:77], v[76:77], v[118:119] op_sel_hi:[1,0]
	v_pk_mul_f32 v[90:91], v[90:91], v[118:119] op_sel_hi:[1,0]
	v_pk_mul_f32 v[82:83], v[82:83], v[118:119] op_sel_hi:[1,0]
	s_waitcnt lgkmcnt(5)
	v_pk_fma_f32 v[0:1], v[0:1], v[70:71], v[8:9]
	v_pk_fma_f32 v[2:3], v[2:3], v[74:75], v[10:11]
	s_waitcnt lgkmcnt(4)
	v_pk_fma_f32 v[4:5], v[4:5], v[72:73], v[12:13]
	v_pk_fma_f32 v[6:7], v[6:7], v[78:79], v[14:15]
	s_waitcnt lgkmcnt(1)
	v_pk_fma_f32 v[8:9], v[16:17], v[76:77], v[24:25]
	v_pk_fma_f32 v[10:11], v[18:19], v[86:87], v[26:27]
	s_waitcnt lgkmcnt(0)
	v_pk_fma_f32 v[12:13], v[82:83], v[20:21], v[28:29]
	v_pk_fma_f32 v[14:15], v[90:91], v[22:23], v[30:31]
	global_store_dwordx4 v[36:37], v[0:3], off nt
	global_store_dwordx4 v[36:37], v[4:7], off offset:1024 nt
	global_store_dwordx4 v[36:37], v[8:11], off offset:2048 nt
	global_store_dwordx4 v[36:37], v[12:15], off offset:3072 nt
	ds_read_b128 v[0:3], v106 offset:12288
	ds_read_b128 v[4:7], v106 offset:13312
	ds_read_b128 v[8:11], v106 offset:28672
	ds_read_b128 v[12:15], v106 offset:29696
	ds_read_b128 v[16:19], v106 offset:14336
	ds_read_b128 v[20:23], v106 offset:15360
	ds_read_b128 v[24:27], v106 offset:30720
	ds_read_b128 v[28:31], v106 offset:31744
	v_pk_mul_f32 v[94:95], v[94:95], v[118:119] op_sel_hi:[1,0]
	v_pk_mul_f32 v[88:89], v[88:89], v[118:119] op_sel_hi:[1,0]
	v_pk_mul_f32 v[98:99], v[98:99], v[118:119] op_sel_hi:[1,0]
	v_pk_mul_f32 v[92:93], v[92:93], v[118:119] op_sel_hi:[1,0]
	v_pk_mul_f32 v[102:103], v[102:103], v[118:119] op_sel_hi:[1,0]
	v_pk_mul_f32 v[96:97], v[96:97], v[118:119] op_sel_hi:[1,0]
	v_pk_mul_f32 v[104:105], v[104:105], v[118:119] op_sel_hi:[1,0]
	v_pk_mul_f32 v[100:101], v[100:101], v[118:119] op_sel_hi:[1,0]
	v_lshl_add_u64 v[34:35], v[34:35], 0, s[6:7]
	s_waitcnt lgkmcnt(5)
	v_pk_fma_f32 v[0:1], v[88:89], v[0:1], v[8:9]
	v_pk_fma_f32 v[2:3], v[94:95], v[2:3], v[10:11]
	s_waitcnt lgkmcnt(4)
	v_pk_fma_f32 v[4:5], v[92:93], v[4:5], v[12:13]
	v_pk_fma_f32 v[6:7], v[98:99], v[6:7], v[14:15]
	s_waitcnt lgkmcnt(1)
	v_pk_fma_f32 v[8:9], v[96:97], v[16:17], v[24:25]
	v_pk_fma_f32 v[10:11], v[102:103], v[18:19], v[26:27]
	s_waitcnt lgkmcnt(0)
	v_pk_fma_f32 v[12:13], v[100:101], v[20:21], v[28:29]
	v_pk_fma_f32 v[14:15], v[104:105], v[22:23], v[30:31]
	global_store_dwordx4 v[40:41], v[0:3], off nt
	global_store_dwordx4 v[40:41], v[4:7], off offset:1024 nt
	global_store_dwordx4 v[40:41], v[8:11], off offset:2048 nt
	global_store_dwordx4 v[40:41], v[12:15], off offset:3072 nt
	s_cbranch_scc1 .LBB0_1658
